# nt (streaming) hint added to the write-through epilogue stores of P1 (PROJ16), P5 (HID16) and P6 (y)
# baseline (speedup 1.0000x reference)
; #define PG8_STAGE(bufoff, gbase, voff) do { _Pragma("unroll") for (int _i = 0; _i < 2; ++_i) \
;         __builtin_amdgcn_global_load_lds((const unsigned*)((const char*)(gbase) + (voff)[_i]), (LAS unsigned*)(lds + (bufoff) + ldsw + _i * 8192), 16, 0, 0); } while (0)
; #define PG8_LDA(dst, b, h) do { _Pragma("unroll") for (int m = 0; m < 4; ++m) _Pragma("unroll") for (int k = 0; k < 2; ++k) dst[m][k] = *(const LAS h16x8*)(lds + PG8_SA(b, h) + aoff + m * 2048 + k * 1024); } while (0)
; #define PG8_LDB(dst, b, h) do { _Pragma("unroll") for (int n = 0; n < 2; ++n) _Pragma("unroll") for (int k = 0; k < 2; ++k) dst[n][k] = *(const LAS h16x8*)(lds + PG8_SB(b, h) + boff + n * 2048 + k * 1024); } while (0)
; #define PG8_MMA(ai, bj, At, Bt) do { __builtin_amdgcn_s_setprio(1); _Pragma("unroll") for (int m = 0; m < 4; ++m) _Pragma("unroll") for (int n = 0; n < 2; ++n) _Pragma("unroll") for (int k = 0; k < 2; ++k) \
;         acc[ai][bj][m][n] = __builtin_amdgcn_mfma_f32_16x16x32_f16(Bt[n][k], At[m][k], acc[ai][bj][m][n], 0, 0, 0); __builtin_amdgcn_s_setprio(0); } while (0)
; #define PG8_WAIT_V(n) asm volatile("s_waitcnt vmcnt(" #n ")" ::: "memory")
; #define PG8_WAIT_L(n) asm volatile("s_waitcnt lgkmcnt(" #n ")" ::: "memory")
; #define PG8_BAR __builtin_amdgcn_s_barrier()
; #define PG8_SCHED __builtin_amdgcn_sched_barrier(0)
; template <class Epi>
; __device__ __forceinline__ void gemm_phase(LAS unsigned char* lds, const Gemm g, const StaticOrder& S, const Epi& E) {
;     ...
;             PG8_LDB(B0, 0, 0); PG8_SCHED; PG8_LDA(At, 0, 0); PG8_STAGE(PG8_SA(1, 1), a1 + hstep, voffA);
;             PG8_WAIT_L(8); PG8_BAR; PG8_WAIT_L(0); PG8_MMA(0, 0, At, B0); PG8_BAR; PG8_SCHED;
;             PG8_LDB(B1, 0, 1); PG8_STAGE(PG8_SB(0, 0), b2, voffB);
;             PG8_BAR; PG8_WAIT_L(0); PG8_MMA(0, 1, At, B1); PG8_BAR;
;             PG8_LDA(At, 0, 1); PG8_STAGE(PG8_SA(0, 0), a2, voffA);
;             PG8_BAR; PG8_WAIT_L(0); PG8_MMA(1, 0, At, B0); PG8_BAR; PG8_SCHED;
;             PG8_STAGE(PG8_SB(0, 1), b2 + hstep, voffB);
;             PG8_WAIT_V(6); PG8_BAR; PG8_MMA(1, 1, At, B1); PG8_BAR;
.LBB0_84:
	ds_read_b128 v[162:165], v158
	ds_read_b128 v[166:169], v158 offset:1024
	ds_read_b128 v[170:173], v158 offset:2048
	ds_read_b128 v[174:177], v158 offset:3072
	s_add_u32 s38, s34, 0xfffc0080
	s_addc_u32 s39, s35, -1
	s_cmp_eq_u32 s96, 12
	s_cselect_b32 s43, s27, s39
	s_cselect_b32 s42, s88, s38
	s_cselect_b32 s39, s25, s95
	s_cselect_b32 s38, s92, s94
	v_lshl_add_u64 v[210:211], s[34:35], 0, v[150:151]
	s_add_i32 m0, s11, 0xc000
	ds_read_b128 v[178:181], v159
	ds_read_b128 v[182:185], v159 offset:1024
	ds_read_b128 v[186:189], v159 offset:2048
	ds_read_b128 v[190:193], v159 offset:3072
	ds_read_b128 v[194:197], v159 offset:4096
	ds_read_b128 v[198:201], v159 offset:5120
	ds_read_b128 v[202:205], v159 offset:6144
	ds_read_b128 v[206:209], v159 offset:7168
	global_load_lds_dwordx4 v[210:211], off
	v_lshl_add_u64 v[210:211], s[34:35], 0, v[152:153]
	s_add_i32 m0, s11, 0xe000
	s_nop 0
	global_load_lds_dwordx4 v[210:211], off
	s_waitcnt lgkmcnt(8)
	s_barrier
	s_waitcnt lgkmcnt(0)
	s_setprio 1
	s_waitcnt lgkmcnt(0)
	v_mfma_f32_16x16x32_f16 v[124:127], v[162:165], v[178:181], v[124:127]
	v_mfma_f32_16x16x32_f16 v[120:123], v[170:173], v[178:181], v[120:123]
	v_mfma_f32_16x16x32_f16 v[116:119], v[162:165], v[186:189], v[116:119]
	v_mfma_f32_16x16x32_f16 v[112:115], v[170:173], v[186:189], v[112:115]
	v_mfma_f32_16x16x32_f16 v[100:103], v[162:165], v[194:197], v[100:103]
	v_mfma_f32_16x16x32_f16 v[96:99], v[170:173], v[194:197], v[96:99]
	v_mfma_f32_16x16x32_f16 v[84:87], v[162:165], v[202:205], v[84:87]
	v_mfma_f32_16x16x32_f16 v[80:83], v[170:173], v[202:205], v[80:83]
	v_mfma_f32_16x16x32_f16 v[124:127], v[166:169], v[182:185], v[124:127]
	v_mfma_f32_16x16x32_f16 v[120:123], v[174:177], v[182:185], v[120:123]
	v_mfma_f32_16x16x32_f16 v[116:119], v[166:169], v[190:193], v[116:119]
	v_mfma_f32_16x16x32_f16 v[112:115], v[174:177], v[190:193], v[112:115]
	v_mfma_f32_16x16x32_f16 v[100:103], v[166:169], v[198:201], v[100:103]
	v_mfma_f32_16x16x32_f16 v[96:99], v[174:177], v[198:201], v[96:99]
	v_mfma_f32_16x16x32_f16 v[84:87], v[166:169], v[206:209], v[84:87]
	v_mfma_f32_16x16x32_f16 v[80:83], v[174:177], v[206:209], v[80:83]
	s_setprio 0
	s_barrier
	s_add_i32 s80, s60, s45
	v_lshl_add_u64 v[222:223], s[38:39], 0, v[128:129]
	s_mov_b32 m0, s80
	ds_read_b128 v[210:213], v160
	ds_read_b128 v[214:217], v160 offset:1024
	ds_read_b128 v[218:221], v160 offset:2048
	ds_read_b128 v[228:231], v160 offset:3072
	global_load_lds_dwordx4 v[222:223], off
	v_lshl_add_u64 v[232:233], s[38:39], 0, v[138:139]
	s_add_i32 m0, s80, 0x2000
	s_nop 0
	global_load_lds_dwordx4 v[232:233], off
	s_barrier
	s_waitcnt lgkmcnt(0)
	s_setprio 1
	s_waitcnt lgkmcnt(0)
	v_mfma_f32_16x16x32_f16 v[108:111], v[210:213], v[178:181], v[108:111]
	v_mfma_f32_16x16x32_f16 v[104:107], v[218:221], v[178:181], v[104:107]
	v_mfma_f32_16x16x32_f16 v[92:95], v[210:213], v[186:189], v[92:95]
	v_mfma_f32_16x16x32_f16 v[88:91], v[218:221], v[186:189], v[88:91]
	v_mfma_f32_16x16x32_f16 v[76:79], v[210:213], v[194:197], v[76:79]
	v_mfma_f32_16x16x32_f16 v[72:75], v[218:221], v[194:197], v[72:75]
	v_mfma_f32_16x16x32_f16 v[68:71], v[210:213], v[202:205], v[68:71]
	v_mfma_f32_16x16x32_f16 v[64:67], v[218:221], v[202:205], v[64:67]
	v_mfma_f32_16x16x32_f16 v[108:111], v[214:217], v[182:185], v[108:111]
	v_mfma_f32_16x16x32_f16 v[104:107], v[228:231], v[182:185], v[104:107]
	v_mfma_f32_16x16x32_f16 v[92:95], v[214:217], v[190:193], v[92:95]
	v_mfma_f32_16x16x32_f16 v[88:91], v[228:231], v[190:193], v[88:91]
	v_mfma_f32_16x16x32_f16 v[76:79], v[214:217], v[198:201], v[76:79]
	v_mfma_f32_16x16x32_f16 v[72:75], v[228:231], v[198:201], v[72:75]
	v_mfma_f32_16x16x32_f16 v[68:71], v[214:217], v[206:209], v[68:71]
	v_mfma_f32_16x16x32_f16 v[64:67], v[228:231], v[206:209], v[64:67]
	s_setprio 0
	s_mov_b32 m0, s11
	v_lshl_add_u64 v[234:235], s[42:43], 0, v[144:145]
	s_barrier
	ds_read_b128 v[178:181], v159 offset:16384
	ds_read_b128 v[182:185], v159 offset:17408
	ds_read_b128 v[186:189], v159 offset:18432
	ds_read_b128 v[190:193], v159 offset:19456
	ds_read_b128 v[194:197], v159 offset:20480
	ds_read_b128 v[198:201], v159 offset:21504
	ds_read_b128 v[202:205], v159 offset:22528
	ds_read_b128 v[206:209], v159 offset:23552
	global_load_lds_dwordx4 v[234:235], off
	v_lshl_add_u64 v[236:237], s[42:43], 0, v[140:141]
	s_mov_b32 m0, s53
	s_nop 0
	global_load_lds_dwordx4 v[236:237], off
	s_barrier
	s_waitcnt lgkmcnt(0)
	s_setprio 1
	s_waitcnt lgkmcnt(0)
	v_mfma_f32_16x16x32_f16 v[60:63], v[162:165], v[178:181], v[60:63]
	v_mfma_f32_16x16x32_f16 v[56:59], v[170:173], v[178:181], v[56:59]
	v_mfma_f32_16x16x32_f16 v[52:55], v[162:165], v[186:189], v[52:55]
	v_mfma_f32_16x16x32_f16 v[48:51], v[170:173], v[186:189], v[48:51]
	v_mfma_f32_16x16x32_f16 v[36:39], v[162:165], v[194:197], v[36:39]
	v_mfma_f32_16x16x32_f16 v[32:35], v[170:173], v[194:197], v[32:35]
	v_mfma_f32_16x16x32_f16 v[20:23], v[162:165], v[202:205], v[20:23]
	v_mfma_f32_16x16x32_f16 v[16:19], v[170:173], v[202:205], v[16:19]
	v_mfma_f32_16x16x32_f16 v[60:63], v[166:169], v[182:185], v[60:63]
	v_mfma_f32_16x16x32_f16 v[56:59], v[174:177], v[182:185], v[56:59]
	v_mfma_f32_16x16x32_f16 v[52:55], v[166:169], v[190:193], v[52:55]
	v_mfma_f32_16x16x32_f16 v[48:51], v[174:177], v[190:193], v[48:51]
	v_mfma_f32_16x16x32_f16 v[36:39], v[166:169], v[198:201], v[36:39]
	v_mfma_f32_16x16x32_f16 v[32:35], v[174:177], v[198:201], v[32:35]
	v_mfma_f32_16x16x32_f16 v[20:23], v[166:169], v[206:209], v[20:23]
	v_mfma_f32_16x16x32_f16 v[16:19], v[174:177], v[206:209], v[16:19]
	s_setprio 0
	s_barrier
; #define PG8_STAGE(bufoff, gbase, voff) do { _Pragma("unroll") for (int _i = 0; _i < 2; ++_i) \
;         __builtin_amdgcn_global_load_lds((const unsigned*)((const char*)(gbase) + (voff)[_i]), (LAS unsigned*)(lds + (bufoff) + ldsw + _i * 8192), 16, 0, 0); } while (0)
; #define PG8_LDA(dst, b, h) do { _Pragma("unroll") for (int m = 0; m < 4; ++m) _Pragma("unroll") for (int k = 0; k < 2; ++k) dst[m][k] = *(const LAS h16x8*)(lds + PG8_SA(b, h) + aoff + m * 2048 + k * 1024); } while (0)
; #define PG8_LDB(dst, b, h) do { _Pragma("unroll") for (int n = 0; n < 2; ++n) _Pragma("unroll") for (int k = 0; k < 2; ++k) dst[n][k] = *(const LAS h16x8*)(lds + PG8_SB(b, h) + boff + n * 2048 + k * 1024); } while (0)
; #define PG8_MMA(ai, bj, At, Bt) do { __builtin_amdgcn_s_setprio(1); _Pragma("unroll") for (int m = 0; m < 4; ++m) _Pragma("unroll") for (int n = 0; n < 2; ++n) _Pragma("unroll") for (int k = 0; k < 2; ++k) \
;         acc[ai][bj][m][n] = __builtin_amdgcn_mfma_f32_16x16x32_f16(Bt[n][k], At[m][k], acc[ai][bj][m][n], 0, 0, 0); __builtin_amdgcn_s_setprio(0); } while (0)
; #define PG8_WAIT_V(n) asm volatile("s_waitcnt vmcnt(" #n ")" ::: "memory")
; #define PG8_WAIT_L(n) asm volatile("s_waitcnt lgkmcnt(" #n ")" ::: "memory")
; #define PG8_BAR __builtin_amdgcn_s_barrier()
; #define PG8_SCHED __builtin_amdgcn_sched_barrier(0)
; template <class Epi>
; __device__ __forceinline__ void gemm_phase(LAS unsigned char* lds, const Gemm g, const StaticOrder& S, const Epi& E) {
;     ...
;             PG8_WAIT_V(6); PG8_BAR; PG8_MMA(1, 1, At, B1); PG8_BAR;
;             PG8_LDB(B0, 1, 0); PG8_SCHED; PG8_LDA(At, 1, 0); PG8_STAGE(PG8_SA(0, 1), a2 + hstep, voffA);
;             PG8_WAIT_L(8); PG8_BAR; PG8_WAIT_L(0); PG8_MMA(0, 0, At, B0); PG8_BAR; PG8_SCHED;
;             PG8_LDB(B1, 1, 1); PG8_STAGE(PG8_SB(1, 0), b3, voffB);
;             PG8_BAR; PG8_WAIT_L(0); PG8_MMA(0, 1, At, B1); PG8_BAR;
;             PG8_LDA(At, 1, 1); PG8_STAGE(PG8_SA(1, 0), a3, voffA);
;             PG8_BAR; PG8_WAIT_L(0); PG8_MMA(1, 0, At, B0); PG8_BAR; PG8_SCHED;
	s_add_u32 vcc_lo, s38, 0x40000
	s_addc_u32 vcc_hi, s39, 0
	s_add_i32 s80, s61, s45
	v_lshl_add_u64 v[162:163], vcc, 0, v[128:129]
	s_mov_b32 m0, s80
	s_nop 0
	global_load_lds_dwordx4 v[162:163], off
	v_lshl_add_u64 v[162:163], vcc, 0, v[138:139]
	s_add_i32 m0, s80, 0x2000
	s_nop 0
	global_load_lds_dwordx4 v[162:163], off
	s_waitcnt vmcnt(6)
	s_barrier
	s_setprio 1
	v_mfma_f32_16x16x32_f16 v[44:47], v[210:213], v[178:181], v[44:47]
	v_mfma_f32_16x16x32_f16 v[40:43], v[218:221], v[178:181], v[40:43]
	v_mfma_f32_16x16x32_f16 v[28:31], v[210:213], v[186:189], v[28:31]
	v_mfma_f32_16x16x32_f16 v[24:27], v[218:221], v[186:189], v[24:27]
	v_mfma_f32_16x16x32_f16 v[12:15], v[210:213], v[194:197], v[12:15]
	v_mfma_f32_16x16x32_f16 v[8:11], v[218:221], v[194:197], v[8:11]
	v_mfma_f32_16x16x32_f16 v[4:7], v[210:213], v[202:205], v[4:7]
	v_mfma_f32_16x16x32_f16 v[0:3], v[218:221], v[202:205], v[0:3]
	v_mfma_f32_16x16x32_f16 v[44:47], v[214:217], v[182:185], v[44:47]
	v_mfma_f32_16x16x32_f16 v[40:43], v[228:231], v[182:185], v[40:43]
	v_mfma_f32_16x16x32_f16 v[28:31], v[214:217], v[190:193], v[28:31]
	v_mfma_f32_16x16x32_f16 v[24:27], v[228:231], v[190:193], v[24:27]
	v_mfma_f32_16x16x32_f16 v[12:15], v[214:217], v[198:201], v[12:15]
	v_mfma_f32_16x16x32_f16 v[8:11], v[228:231], v[198:201], v[8:11]
	v_mfma_f32_16x16x32_f16 v[4:7], v[214:217], v[206:209], v[4:7]
	v_mfma_f32_16x16x32_f16 v[0:3], v[228:231], v[206:209], v[0:3]
	s_setprio 0
	s_add_i32 s80, 0, 0x18000
	v_add_u32_e32 v161, s80, v137
	s_barrier
	ds_read_b128 v[162:165], v161
	ds_read_b128 v[166:169], v161 offset:1024
	ds_read_b128 v[170:173], v161 offset:2048
	ds_read_b128 v[174:177], v161 offset:3072
	s_add_u32 s42, s42, 0x40000
	s_addc_u32 s43, s43, 0
	s_mov_b32 m0, s54
	v_lshl_add_u64 v[210:211], s[42:43], 0, v[144:145]
	ds_read_b128 v[178:181], v159 offset:32768
	ds_read_b128 v[182:185], v159 offset:33792
	ds_read_b128 v[186:189], v159 offset:34816
	ds_read_b128 v[190:193], v159 offset:35840
	ds_read_b128 v[194:197], v159 offset:36864
	ds_read_b128 v[198:201], v159 offset:37888
	ds_read_b128 v[202:205], v159 offset:38912
	ds_read_b128 v[206:209], v159 offset:39936
	global_load_lds_dwordx4 v[210:211], off
	v_lshl_add_u64 v[210:211], s[42:43], 0, v[140:141]
	s_mov_b32 m0, s55
	s_nop 0
	global_load_lds_dwordx4 v[210:211], off
	s_waitcnt lgkmcnt(8)
	s_barrier
	s_waitcnt lgkmcnt(0)
	s_setprio 1
	s_waitcnt lgkmcnt(0)
	v_mfma_f32_16x16x32_f16 v[124:127], v[162:165], v[178:181], v[124:127]
	v_mfma_f32_16x16x32_f16 v[120:123], v[170:173], v[178:181], v[120:123]
	v_mfma_f32_16x16x32_f16 v[116:119], v[162:165], v[186:189], v[116:119]
	v_mfma_f32_16x16x32_f16 v[112:115], v[170:173], v[186:189], v[112:115]
	v_mfma_f32_16x16x32_f16 v[100:103], v[162:165], v[194:197], v[100:103]
	v_mfma_f32_16x16x32_f16 v[96:99], v[170:173], v[194:197], v[96:99]
	v_mfma_f32_16x16x32_f16 v[84:87], v[162:165], v[202:205], v[84:87]
	v_mfma_f32_16x16x32_f16 v[80:83], v[170:173], v[202:205], v[80:83]
	v_mfma_f32_16x16x32_f16 v[124:127], v[166:169], v[182:185], v[124:127]
	v_mfma_f32_16x16x32_f16 v[120:123], v[174:177], v[182:185], v[120:123]
	v_mfma_f32_16x16x32_f16 v[116:119], v[166:169], v[190:193], v[116:119]
	v_mfma_f32_16x16x32_f16 v[112:115], v[174:177], v[190:193], v[112:115]
	v_mfma_f32_16x16x32_f16 v[100:103], v[166:169], v[198:201], v[100:103]
	v_mfma_f32_16x16x32_f16 v[96:99], v[174:177], v[198:201], v[96:99]
	v_mfma_f32_16x16x32_f16 v[84:87], v[166:169], v[206:209], v[84:87]
	v_mfma_f32_16x16x32_f16 v[80:83], v[174:177], v[206:209], v[80:83]
	s_setprio 0
	s_barrier
	s_add_i32 s42, 0, 0x1c000
	s_add_i32 s43, s80, s45
	v_add_u32_e32 v161, s42, v137
	v_lshl_add_u64 v[222:223], v[222:223], 0, s[0:1]
	s_mov_b32 m0, s43
	ds_read_b128 v[210:213], v161
	ds_read_b128 v[214:217], v161 offset:1024
	ds_read_b128 v[218:221], v161 offset:2048
	ds_read_b128 v[228:231], v161 offset:3072
	global_load_lds_dwordx4 v[222:223], off
	v_lshl_add_u64 v[222:223], v[232:233], 0, s[0:1]
	s_add_i32 m0, s43, 0x2000
	s_nop 0
	global_load_lds_dwordx4 v[222:223], off
	s_barrier
	s_waitcnt lgkmcnt(0)
	s_setprio 1
	s_waitcnt lgkmcnt(0)
	v_mfma_f32_16x16x32_f16 v[108:111], v[210:213], v[178:181], v[108:111]
	v_mfma_f32_16x16x32_f16 v[104:107], v[218:221], v[178:181], v[104:107]
	v_mfma_f32_16x16x32_f16 v[92:95], v[210:213], v[186:189], v[92:95]
	v_mfma_f32_16x16x32_f16 v[88:91], v[218:221], v[186:189], v[88:91]
	v_mfma_f32_16x16x32_f16 v[76:79], v[210:213], v[194:197], v[76:79]
	v_mfma_f32_16x16x32_f16 v[72:75], v[218:221], v[194:197], v[72:75]
	v_mfma_f32_16x16x32_f16 v[68:71], v[210:213], v[202:205], v[68:71]
	v_mfma_f32_16x16x32_f16 v[64:67], v[218:221], v[202:205], v[64:67]
	v_mfma_f32_16x16x32_f16 v[108:111], v[214:217], v[182:185], v[108:111]
	v_mfma_f32_16x16x32_f16 v[104:107], v[228:231], v[182:185], v[104:107]
	v_mfma_f32_16x16x32_f16 v[92:95], v[214:217], v[190:193], v[92:95]
	v_mfma_f32_16x16x32_f16 v[88:91], v[228:231], v[190:193], v[88:91]
	v_mfma_f32_16x16x32_f16 v[76:79], v[214:217], v[198:201], v[76:79]
	v_mfma_f32_16x16x32_f16 v[72:75], v[228:231], v[198:201], v[72:75]
	v_mfma_f32_16x16x32_f16 v[68:71], v[214:217], v[206:209], v[68:71]
	v_mfma_f32_16x16x32_f16 v[64:67], v[228:231], v[206:209], v[64:67]
	s_setprio 0
	s_mov_b32 m0, s56
	v_lshl_add_u64 v[222:223], v[234:235], 0, s[0:1]
	s_barrier
	ds_read_b128 v[178:181], v159 offset:49152
	ds_read_b128 v[182:185], v159 offset:50176
	ds_read_b128 v[186:189], v159 offset:51200
	ds_read_b128 v[190:193], v159 offset:52224
	ds_read_b128 v[194:197], v159 offset:53248
	ds_read_b128 v[198:201], v159 offset:54272
	ds_read_b128 v[202:205], v159 offset:55296
	ds_read_b128 v[206:209], v159 offset:56320
	global_load_lds_dwordx4 v[222:223], off
	v_lshl_add_u64 v[222:223], v[236:237], 0, s[0:1]
	s_mov_b32 m0, s57
	s_nop 0
	global_load_lds_dwordx4 v[222:223], off
	s_barrier
; #define PG8_WAIT_V(n) asm volatile("s_waitcnt vmcnt(" #n ")" ::: "memory")
; #define PG8_WAIT_L(n) asm volatile("s_waitcnt lgkmcnt(" #n ")" ::: "memory")
; #define PG8_BAR __builtin_amdgcn_s_barrier()
; #define PG8_SCHED __builtin_amdgcn_sched_barrier(0)
; template <class Epi>
; __device__ __forceinline__ void gemm_phase(LAS unsigned char* lds, const Gemm g, const StaticOrder& S, const Epi& E) {
;     ...
;             PG8_BAR; PG8_WAIT_L(0); PG8_MMA(1, 0, At, B0); PG8_BAR; PG8_SCHED;
;             PG8_STAGE(PG8_SB(1, 1), b3 + hstep, voffB);
;             PG8_WAIT_V(6); PG8_BAR; PG8_MMA(1, 1, At, B1); PG8_BAR;
;     __device__ __forceinline__ void operator()(const f32x4 (&acc)[2][2][4][2], const pg8::Unit& u, int wr, int wc, int fr, int fq) const {
;         const int row0 = u.pm * 256 + wr * 64 + fr, col0 = u.pn * 256 + wc * 32 + 8 * fq;
; #pragma unroll
;         for (int ai = 0; ai < 2; ++ai)
; #pragma unroll
;             for (int m = 0; m < 4; ++m) {
;                 const int row = row0 + ai * 128 + m * 16;
;                 float ss = 0.f, rstd = 1.f;
;                 if (MODE == 2) rstd = rsqrtf(rowss[row] * (1.f / 1024.f) + EPS);
; #pragma unroll
;                 for (int bj = 0; bj < 2; ++bj) {
;                     const int c = col0 + bj * 128;
;                     f32x4 v0 = acc[ai][bj][m][0], v1 = acc[ai][bj][m][1];
;                     if (MODE == 1) {
;                         const float* rp = res + (size_t)row * ldres + c;
;                         v0 += *(const f32x4*)rp; v1 += *(const f32x4*)(rp + 4);
;                     }
;                     if (MODE == 3) {
;                         const h16x8 r8 = *(const h16x8*)(res16 + (size_t)row * ldres + c);
; #pragma unroll
;                         for (int j = 0; j < 4; ++j) { v0[j] += (float)r8[j]; v1[j] += (float)r8[4 + j]; }
;                     }
;                     if (MODE == 1 || MODE == 3) {
;                         ss += v0[0] * v0[0] + v0[1] * v0[1] + v0[2] * v0[2] + v0[3] * v0[3] + v1[0] * v1[0] + v1[1] * v1[1] + v1[2] * v1[2] + v1[3] * v1[3];
;                     }
;                     if (MODE == 2) {
; #pragma unroll
;                         for (int j = 0; j < 4; ++j) { float a = fmaxf(v0[j] * rstd, 0.f), b = fmaxf(v1[j] * rstd, 0.f); v0[j] = a * a; v1[j] = b * b; }
;                     }
;                     *(h16x8*)(o16 + (size_t)row * ld16 + c) = pack8(v0, v1);
	s_waitcnt lgkmcnt(0)
	s_setprio 1
	s_waitcnt lgkmcnt(0)
	v_mfma_f32_16x16x32_f16 v[60:63], v[162:165], v[178:181], v[60:63]
	v_mfma_f32_16x16x32_f16 v[56:59], v[170:173], v[178:181], v[56:59]
	v_mfma_f32_16x16x32_f16 v[52:55], v[162:165], v[186:189], v[52:55]
	v_mfma_f32_16x16x32_f16 v[48:51], v[170:173], v[186:189], v[48:51]
	v_mfma_f32_16x16x32_f16 v[36:39], v[162:165], v[194:197], v[36:39]
	v_mfma_f32_16x16x32_f16 v[32:35], v[170:173], v[194:197], v[32:35]
	v_mfma_f32_16x16x32_f16 v[20:23], v[162:165], v[202:205], v[20:23]
	v_mfma_f32_16x16x32_f16 v[16:19], v[170:173], v[202:205], v[16:19]
	v_mfma_f32_16x16x32_f16 v[60:63], v[166:169], v[182:185], v[60:63]
	v_mfma_f32_16x16x32_f16 v[56:59], v[174:177], v[182:185], v[56:59]
	v_mfma_f32_16x16x32_f16 v[52:55], v[166:169], v[190:193], v[52:55]
	v_mfma_f32_16x16x32_f16 v[48:51], v[174:177], v[190:193], v[48:51]
	v_mfma_f32_16x16x32_f16 v[36:39], v[166:169], v[198:201], v[36:39]
	v_mfma_f32_16x16x32_f16 v[32:35], v[174:177], v[198:201], v[32:35]
	v_mfma_f32_16x16x32_f16 v[20:23], v[166:169], v[206:209], v[20:23]
	v_mfma_f32_16x16x32_f16 v[16:19], v[174:177], v[206:209], v[16:19]
	s_setprio 0
	s_barrier
	s_add_u32 s38, s38, 0x40080
	s_addc_u32 s39, s39, 0
	s_add_i32 s42, s42, s45
	v_lshl_add_u64 v[162:163], s[38:39], 0, v[128:129]
	s_mov_b32 m0, s42
	s_nop 0
	global_load_lds_dwordx4 v[162:163], off
	v_lshl_add_u64 v[162:163], s[38:39], 0, v[138:139]
	s_add_i32 m0, s42, 0x2000
	s_nop 0
	global_load_lds_dwordx4 v[162:163], off
	s_waitcnt vmcnt(6)
	s_barrier
	s_setprio 1
	v_mfma_f32_16x16x32_f16 v[44:47], v[210:213], v[178:181], v[44:47]
	v_mfma_f32_16x16x32_f16 v[40:43], v[218:221], v[178:181], v[40:43]
	v_mfma_f32_16x16x32_f16 v[28:31], v[210:213], v[186:189], v[28:31]
	v_mfma_f32_16x16x32_f16 v[24:27], v[218:221], v[186:189], v[24:27]
	v_mfma_f32_16x16x32_f16 v[12:15], v[210:213], v[194:197], v[12:15]
	v_mfma_f32_16x16x32_f16 v[8:11], v[218:221], v[194:197], v[8:11]
	v_mfma_f32_16x16x32_f16 v[4:7], v[210:213], v[202:205], v[4:7]
	v_mfma_f32_16x16x32_f16 v[0:3], v[218:221], v[202:205], v[0:3]
	v_mfma_f32_16x16x32_f16 v[44:47], v[214:217], v[182:185], v[44:47]
	v_mfma_f32_16x16x32_f16 v[40:43], v[228:231], v[182:185], v[40:43]
	v_mfma_f32_16x16x32_f16 v[28:31], v[214:217], v[190:193], v[28:31]
	v_mfma_f32_16x16x32_f16 v[24:27], v[228:231], v[190:193], v[24:27]
	v_mfma_f32_16x16x32_f16 v[12:15], v[214:217], v[198:201], v[12:15]
	v_mfma_f32_16x16x32_f16 v[8:11], v[228:231], v[198:201], v[8:11]
	v_mfma_f32_16x16x32_f16 v[4:7], v[214:217], v[206:209], v[4:7]
	v_mfma_f32_16x16x32_f16 v[0:3], v[228:231], v[206:209], v[0:3]
	s_setprio 0
	s_add_i32 s96, s96, 2
	s_add_u32 s34, s34, 0x100
	s_addc_u32 s35, s35, 0
	s_add_u32 s94, s94, 0x100
	s_addc_u32 s95, s95, 0
	s_cmp_gt_u32 s96, 13
	s_barrier
	s_cbranch_scc0 .LBB0_84
	v_lshl_add_u32 v161, s10, 8, v135
	v_lshl_or_b32 v162, s63, 8, v143
	v_and_b32_e32 v164, 0x60, v143
	v_add_lshl_u32 v162, v162, v164, 1
	v_mov_b32_e32 v163, 0
	v_mov_b64_e32 v[166:167], s[90:91]
	v_mad_i64_i32 v[164:165], s[34:35], v161, s62, v[166:167]
	v_lshl_add_u64 v[164:165], v[164:165], 0, v[162:163]
	v_and_b32_e32 v168, 8, v135
	v_cmp_eq_u32_e64 s[98:99], 0, v168
	v_mov_b32_e32 v168, 0xffff1040
	v_cndmask_b32_e64 v170, v168, 0, s[98:99]
	v_cndmask_b32_e64 v171, -1, 0, s[98:99]
	v_mov_b32_e32 v168, 0xf040
	v_cndmask_b32_e64 v172, 0, v168, s[98:99]
	v_mov_b32_e32 v173, 0
	s_mov_b32 s100, 0x1e000
	s_mov_b32 s101, 0
	v_cvt_pk_f16_f32 v124, v124, v125
	v_cvt_pk_f16_f32 v125, v126, v127
	v_cvt_pk_f16_f32 v126, v120, v121
	v_cvt_pk_f16_f32 v127, v122, v123
	v_cvt_pk_f16_f32 v108, v108, v109
	v_cvt_pk_f16_f32 v109, v110, v111
	v_cvt_pk_f16_f32 v110, v104, v105
	v_cvt_pk_f16_f32 v111, v106, v107
	s_nop 1
	v_mov_b32_dpp v176, v108 row_ror:8 row_mask:0xf bank_mask:0xf
	v_mov_b32_dpp v177, v109 row_ror:8 row_mask:0xf bank_mask:0xf
	v_mov_b32_dpp v178, v110 row_ror:8 row_mask:0xf bank_mask:0xf
	v_mov_b32_dpp v179, v111 row_ror:8 row_mask:0xf bank_mask:0xf
	v_cndmask_b32_e64 v108, v176, v124, s[98:99]
	v_cndmask_b32_e64 v109, v177, v125, s[98:99]
	v_cndmask_b32_e64 v110, v178, v126, s[98:99]
	v_cndmask_b32_e64 v111, v179, v127, s[98:99]
	v_cndmask_b32_e64 v176, v124, v176, s[98:99]
	v_cndmask_b32_e64 v177, v125, v177, s[98:99]
	v_cndmask_b32_e64 v178, v126, v178, s[98:99]
	v_cndmask_b32_e64 v179, v127, v179, s[98:99]
	v_lshl_add_u64 v[180:181], v[164:165], 0, v[170:171]
	v_lshl_add_u64 v[182:183], v[164:165], 0, v[172:173]
	global_store_dwordx4 v[180:181], v[108:111], off sc0 sc1 nt
	global_store_dwordx4 v[182:183], v[176:179], off sc0 sc1 nt
	v_lshl_add_u64 v[164:165], v[164:165], 0, s[100:101]
	v_cvt_pk_f16_f32 v116, v116, v117
	v_cvt_pk_f16_f32 v117, v118, v119
	v_cvt_pk_f16_f32 v118, v112, v113
	v_cvt_pk_f16_f32 v119, v114, v115
	v_cvt_pk_f16_f32 v92, v92, v93
	v_cvt_pk_f16_f32 v93, v94, v95
	v_cvt_pk_f16_f32 v94, v88, v89
	v_cvt_pk_f16_f32 v95, v90, v91
	s_nop 1
	v_mov_b32_dpp v184, v92 row_ror:8 row_mask:0xf bank_mask:0xf
	v_mov_b32_dpp v185, v93 row_ror:8 row_mask:0xf bank_mask:0xf
	v_mov_b32_dpp v186, v94 row_ror:8 row_mask:0xf bank_mask:0xf
	v_mov_b32_dpp v187, v95 row_ror:8 row_mask:0xf bank_mask:0xf
	v_cndmask_b32_e64 v92, v184, v116, s[98:99]
	v_cndmask_b32_e64 v93, v185, v117, s[98:99]
	v_cndmask_b32_e64 v94, v186, v118, s[98:99]
	v_cndmask_b32_e64 v95, v187, v119, s[98:99]
	v_cndmask_b32_e64 v184, v116, v184, s[98:99]
	v_cndmask_b32_e64 v185, v117, v185, s[98:99]
	v_cndmask_b32_e64 v186, v118, v186, s[98:99]
	v_cndmask_b32_e64 v187, v119, v187, s[98:99]
	v_lshl_add_u64 v[188:189], v[164:165], 0, v[170:171]
	v_lshl_add_u64 v[190:191], v[164:165], 0, v[172:173]
;     __device__ __forceinline__ void operator()(const f32x4 (&acc)[2][2][4][2], const pg8::Unit& u, int wr, int wc, int fr, int fq) const {
;         const int row0 = u.pm * 256 + wr * 64 + fr, col0 = u.pn * 256 + wc * 32 + 8 * fq;
; #pragma unroll
;         for (int ai = 0; ai < 2; ++ai)
; #pragma unroll
;             for (int m = 0; m < 4; ++m) {
;                 const int row = row0 + ai * 128 + m * 16;
;                 float ss = 0.f, rstd = 1.f;
;                 if (MODE == 2) rstd = rsqrtf(rowss[row] * (1.f / 1024.f) + EPS);
; #pragma unroll
;                 for (int bj = 0; bj < 2; ++bj) {
;                     const int c = col0 + bj * 128;
;                     f32x4 v0 = acc[ai][bj][m][0], v1 = acc[ai][bj][m][1];
;                     if (MODE == 1) {
;                         const float* rp = res + (size_t)row * ldres + c;
;                         v0 += *(const f32x4*)rp; v1 += *(const f32x4*)(rp + 4);
;                     }
;                     if (MODE == 3) {
;                         const h16x8 r8 = *(const h16x8*)(res16 + (size_t)row * ldres + c);
; #pragma unroll
;                         for (int j = 0; j < 4; ++j) { v0[j] += (float)r8[j]; v1[j] += (float)r8[4 + j]; }
;                     }
;                     if (MODE == 1 || MODE == 3) {
;                         ss += v0[0] * v0[0] + v0[1] * v0[1] + v0[2] * v0[2] + v0[3] * v0[3] + v1[0] * v1[0] + v1[1] * v1[1] + v1[2] * v1[2] + v1[3] * v1[3];
;                     }
;                     if (MODE == 2) {
; #pragma unroll
;                         for (int j = 0; j < 4; ++j) { float a = fmaxf(v0[j] * rstd, 0.f), b = fmaxf(v1[j] * rstd, 0.f); v0[j] = a * a; v1[j] = b * b; }
;                     }
;                     *(h16x8*)(o16 + (size_t)row * ld16 + c) = pack8(v0, v1);
	global_store_dwordx4 v[188:189], v[92:95], off sc0 sc1 nt
	global_store_dwordx4 v[190:191], v[184:187], off sc0 sc1 nt
	v_lshl_add_u64 v[164:165], v[164:165], 0, s[100:101]
	v_cvt_pk_f16_f32 v100, v100, v101
	v_cvt_pk_f16_f32 v101, v102, v103
	v_cvt_pk_f16_f32 v102, v96, v97
	v_cvt_pk_f16_f32 v103, v98, v99
	v_cvt_pk_f16_f32 v76, v76, v77
	v_cvt_pk_f16_f32 v77, v78, v79
	v_cvt_pk_f16_f32 v78, v72, v73
	v_cvt_pk_f16_f32 v79, v74, v75
	s_nop 1
	v_mov_b32_dpp v176, v76 row_ror:8 row_mask:0xf bank_mask:0xf
	v_mov_b32_dpp v177, v77 row_ror:8 row_mask:0xf bank_mask:0xf
	v_mov_b32_dpp v178, v78 row_ror:8 row_mask:0xf bank_mask:0xf
	v_mov_b32_dpp v179, v79 row_ror:8 row_mask:0xf bank_mask:0xf
	v_cndmask_b32_e64 v76, v176, v100, s[98:99]
	v_cndmask_b32_e64 v77, v177, v101, s[98:99]
	v_cndmask_b32_e64 v78, v178, v102, s[98:99]
	v_cndmask_b32_e64 v79, v179, v103, s[98:99]
	v_cndmask_b32_e64 v176, v100, v176, s[98:99]
	v_cndmask_b32_e64 v177, v101, v177, s[98:99]
	v_cndmask_b32_e64 v178, v102, v178, s[98:99]
	v_cndmask_b32_e64 v179, v103, v179, s[98:99]
	v_lshl_add_u64 v[180:181], v[164:165], 0, v[170:171]
	v_lshl_add_u64 v[182:183], v[164:165], 0, v[172:173]
	global_store_dwordx4 v[180:181], v[76:79], off sc0 sc1 nt
	global_store_dwordx4 v[182:183], v[176:179], off sc0 sc1 nt
	v_lshl_add_u64 v[164:165], v[164:165], 0, s[100:101]
	v_cvt_pk_f16_f32 v84, v84, v85
	v_cvt_pk_f16_f32 v85, v86, v87
	v_cvt_pk_f16_f32 v86, v80, v81
	v_cvt_pk_f16_f32 v87, v82, v83
	v_cvt_pk_f16_f32 v68, v68, v69
	v_cvt_pk_f16_f32 v69, v70, v71
	v_cvt_pk_f16_f32 v70, v64, v65
	v_cvt_pk_f16_f32 v71, v66, v67
	s_nop 1
	v_mov_b32_dpp v184, v68 row_ror:8 row_mask:0xf bank_mask:0xf
	v_mov_b32_dpp v185, v69 row_ror:8 row_mask:0xf bank_mask:0xf
	v_mov_b32_dpp v186, v70 row_ror:8 row_mask:0xf bank_mask:0xf
	v_mov_b32_dpp v187, v71 row_ror:8 row_mask:0xf bank_mask:0xf
	v_cndmask_b32_e64 v68, v184, v84, s[98:99]
	v_cndmask_b32_e64 v69, v185, v85, s[98:99]
	v_cndmask_b32_e64 v70, v186, v86, s[98:99]
	v_cndmask_b32_e64 v71, v187, v87, s[98:99]
	v_cndmask_b32_e64 v184, v84, v184, s[98:99]
	v_cndmask_b32_e64 v185, v85, v185, s[98:99]
	v_cndmask_b32_e64 v186, v86, v186, s[98:99]
	v_cndmask_b32_e64 v187, v87, v187, s[98:99]
	v_lshl_add_u64 v[188:189], v[164:165], 0, v[170:171]
	v_lshl_add_u64 v[190:191], v[164:165], 0, v[172:173]
	global_store_dwordx4 v[188:189], v[68:71], off sc0 sc1 nt
	global_store_dwordx4 v[190:191], v[184:187], off sc0 sc1 nt
	v_add_co_u32_e32 v164, vcc, 0x96000, v164
	s_nop 1
	v_addc_co_u32_e32 v165, vcc, 0, v165, vcc
	v_cvt_pk_f16_f32 v60, v60, v61
	v_cvt_pk_f16_f32 v61, v62, v63
	v_cvt_pk_f16_f32 v62, v56, v57
	v_cvt_pk_f16_f32 v63, v58, v59
	v_cvt_pk_f16_f32 v44, v44, v45
	v_cvt_pk_f16_f32 v45, v46, v47
	v_cvt_pk_f16_f32 v46, v40, v41
	v_cvt_pk_f16_f32 v47, v42, v43
	s_nop 1
	v_mov_b32_dpp v176, v44 row_ror:8 row_mask:0xf bank_mask:0xf
	v_mov_b32_dpp v177, v45 row_ror:8 row_mask:0xf bank_mask:0xf
	v_mov_b32_dpp v178, v46 row_ror:8 row_mask:0xf bank_mask:0xf
	v_mov_b32_dpp v179, v47 row_ror:8 row_mask:0xf bank_mask:0xf
	v_cndmask_b32_e64 v44, v176, v60, s[98:99]
	v_cndmask_b32_e64 v45, v177, v61, s[98:99]
	v_cndmask_b32_e64 v46, v178, v62, s[98:99]
	v_cndmask_b32_e64 v47, v179, v63, s[98:99]
	v_cndmask_b32_e64 v176, v60, v176, s[98:99]
	v_cndmask_b32_e64 v177, v61, v177, s[98:99]
	v_cndmask_b32_e64 v178, v62, v178, s[98:99]
	v_cndmask_b32_e64 v179, v63, v179, s[98:99]
	v_lshl_add_u64 v[180:181], v[164:165], 0, v[170:171]
	v_lshl_add_u64 v[182:183], v[164:165], 0, v[172:173]
	global_store_dwordx4 v[180:181], v[44:47], off sc0 sc1 nt
	global_store_dwordx4 v[182:183], v[176:179], off sc0 sc1 nt
; template <class Epi>
; __device__ __forceinline__ void gemm_phase(LAS unsigned char* lds, const Gemm g, const StaticOrder& S, const Epi& E) {
;     ...
;         if constexpr (!Epi::AFTER_DRAIN) E(acc, cur, wr, wc, fr, fq);
;         if (!has_next) break;
; #pragma unroll
;         for (int a = 0; a < 2; ++a)
; #pragma unroll
;             for (int b = 0; b < 2; ++b)
; #pragma unroll
;                 for (int m = 0; m < 4; ++m)
; #pragma unroll
;                     for (int n = 0; n < 2; ++n) acc[a][b][m][n] = (f32x4){0.f, 0.f, 0.f, 0.f};
;         cur = nxt; cA = nA; cB = nB; ++ui;
;     }
;     PG8_WAIT_V(0);
;     __device__ __forceinline__ void operator()(const f32x4 (&acc)[2][2][4][2], const pg8::Unit& u, int wr, int wc, int fr, int fq) const {
;         const int row0 = u.pm * 256 + wr * 64 + fr, col0 = u.pn * 256 + wc * 32 + 8 * fq;
; #pragma unroll
;         for (int ai = 0; ai < 2; ++ai)
; #pragma unroll
;             for (int m = 0; m < 4; ++m) {
;                 const int row = row0 + ai * 128 + m * 16;
;                 float ss = 0.f, rstd = 1.f;
;                 if (MODE == 2) rstd = rsqrtf(rowss[row] * (1.f / 1024.f) + EPS);
; #pragma unroll
;                 for (int bj = 0; bj < 2; ++bj) {
;                     const int c = col0 + bj * 128;
;                     f32x4 v0 = acc[ai][bj][m][0], v1 = acc[ai][bj][m][1];
;                     if (MODE == 1) {
;                         const float* rp = res + (size_t)row * ldres + c;
;                         v0 += *(const f32x4*)rp; v1 += *(const f32x4*)(rp + 4);
;                     }
;                     if (MODE == 3) {
;                         const h16x8 r8 = *(const h16x8*)(res16 + (size_t)row * ldres + c);
; #pragma unroll
;                         for (int j = 0; j < 4; ++j) { v0[j] += (float)r8[j]; v1[j] += (float)r8[4 + j]; }
;                     }
;                     if (MODE == 1 || MODE == 3) {
;                         ss += v0[0] * v0[0] + v0[1] * v0[1] + v0[2] * v0[2] + v0[3] * v0[3] + v1[0] * v1[0] + v1[1] * v1[1] + v1[2] * v1[2] + v1[3] * v1[3];
;                     }
;                     if (MODE == 2) {
; #pragma unroll
;                         for (int j = 0; j < 4; ++j) { float a = fmaxf(v0[j] * rstd, 0.f), b = fmaxf(v1[j] * rstd, 0.f); v0[j] = a * a; v1[j] = b * b; }
;                     }
;                     *(h16x8*)(o16 + (size_t)row * ld16 + c) = pack8(v0, v1);
	v_lshl_add_u64 v[164:165], v[164:165], 0, s[100:101]
	v_cvt_pk_f16_f32 v52, v52, v53
	v_cvt_pk_f16_f32 v53, v54, v55
	v_cvt_pk_f16_f32 v54, v48, v49
	v_cvt_pk_f16_f32 v55, v50, v51
	v_cvt_pk_f16_f32 v28, v28, v29
	v_cvt_pk_f16_f32 v29, v30, v31
	v_cvt_pk_f16_f32 v30, v24, v25
	v_cvt_pk_f16_f32 v31, v26, v27
	s_nop 1
	v_mov_b32_dpp v184, v28 row_ror:8 row_mask:0xf bank_mask:0xf
	v_mov_b32_dpp v185, v29 row_ror:8 row_mask:0xf bank_mask:0xf
	v_mov_b32_dpp v186, v30 row_ror:8 row_mask:0xf bank_mask:0xf
	v_mov_b32_dpp v187, v31 row_ror:8 row_mask:0xf bank_mask:0xf
	v_cndmask_b32_e64 v28, v184, v52, s[98:99]
	v_cndmask_b32_e64 v29, v185, v53, s[98:99]
	v_cndmask_b32_e64 v30, v186, v54, s[98:99]
	v_cndmask_b32_e64 v31, v187, v55, s[98:99]
	v_cndmask_b32_e64 v184, v52, v184, s[98:99]
	v_cndmask_b32_e64 v185, v53, v185, s[98:99]
	v_cndmask_b32_e64 v186, v54, v186, s[98:99]
	v_cndmask_b32_e64 v187, v55, v187, s[98:99]
	v_lshl_add_u64 v[188:189], v[164:165], 0, v[170:171]
	v_lshl_add_u64 v[190:191], v[164:165], 0, v[172:173]
	global_store_dwordx4 v[188:189], v[28:31], off sc0 sc1 nt
	global_store_dwordx4 v[190:191], v[184:187], off sc0 sc1 nt
	v_lshl_add_u64 v[164:165], v[164:165], 0, s[100:101]
	v_cvt_pk_f16_f32 v36, v36, v37
	v_cvt_pk_f16_f32 v37, v38, v39
	v_cvt_pk_f16_f32 v38, v32, v33
	v_cvt_pk_f16_f32 v39, v34, v35
	v_cvt_pk_f16_f32 v12, v12, v13
	v_cvt_pk_f16_f32 v13, v14, v15
	v_cvt_pk_f16_f32 v14, v8, v9
	v_cvt_pk_f16_f32 v15, v10, v11
	s_nop 1
	v_mov_b32_dpp v176, v12 row_ror:8 row_mask:0xf bank_mask:0xf
	v_mov_b32_dpp v177, v13 row_ror:8 row_mask:0xf bank_mask:0xf
	v_mov_b32_dpp v178, v14 row_ror:8 row_mask:0xf bank_mask:0xf
	v_mov_b32_dpp v179, v15 row_ror:8 row_mask:0xf bank_mask:0xf
	v_cndmask_b32_e64 v12, v176, v36, s[98:99]
	v_cndmask_b32_e64 v13, v177, v37, s[98:99]
	v_cndmask_b32_e64 v14, v178, v38, s[98:99]
	v_cndmask_b32_e64 v15, v179, v39, s[98:99]
	v_cndmask_b32_e64 v176, v36, v176, s[98:99]
	v_cndmask_b32_e64 v177, v37, v177, s[98:99]
	v_cndmask_b32_e64 v178, v38, v178, s[98:99]
	v_cndmask_b32_e64 v179, v39, v179, s[98:99]
	v_lshl_add_u64 v[180:181], v[164:165], 0, v[170:171]
	v_lshl_add_u64 v[182:183], v[164:165], 0, v[172:173]
	global_store_dwordx4 v[180:181], v[12:15], off sc0 sc1 nt
	global_store_dwordx4 v[182:183], v[176:179], off sc0 sc1 nt
	v_lshl_add_u64 v[164:165], v[164:165], 0, s[100:101]
	v_cvt_pk_f16_f32 v20, v20, v21
	v_cvt_pk_f16_f32 v21, v22, v23
	v_cvt_pk_f16_f32 v22, v16, v17
	v_cvt_pk_f16_f32 v23, v18, v19
	v_cvt_pk_f16_f32 v4, v4, v5
	v_cvt_pk_f16_f32 v5, v6, v7
	v_cvt_pk_f16_f32 v6, v0, v1
	v_cvt_pk_f16_f32 v7, v2, v3
	s_nop 1
	v_mov_b32_dpp v184, v4 row_ror:8 row_mask:0xf bank_mask:0xf
	v_mov_b32_dpp v185, v5 row_ror:8 row_mask:0xf bank_mask:0xf
	v_mov_b32_dpp v186, v6 row_ror:8 row_mask:0xf bank_mask:0xf
	v_mov_b32_dpp v187, v7 row_ror:8 row_mask:0xf bank_mask:0xf
	v_cndmask_b32_e64 v4, v184, v20, s[98:99]
	v_cndmask_b32_e64 v5, v185, v21, s[98:99]
	v_cndmask_b32_e64 v6, v186, v22, s[98:99]
	v_cndmask_b32_e64 v7, v187, v23, s[98:99]
	v_cndmask_b32_e64 v184, v20, v184, s[98:99]
	v_cndmask_b32_e64 v185, v21, v185, s[98:99]
	v_cndmask_b32_e64 v186, v22, v186, s[98:99]
	v_cndmask_b32_e64 v187, v23, v187, s[98:99]
	v_lshl_add_u64 v[188:189], v[164:165], 0, v[170:171]
	v_lshl_add_u64 v[190:191], v[164:165], 0, v[172:173]
	global_store_dwordx4 v[188:189], v[4:7], off sc0 sc1 nt
	global_store_dwordx4 v[190:191], v[184:187], off sc0 sc1 nt
	s_and_b64 vcc, exec, s[8:9]
	s_mov_b32 s63, s24
	s_mov_b32 s10, s26
	s_mov_b64 s[38:39], s[30:31]
	s_mov_b64 s[34:35], s[28:29]
	s_cbranch_vccz .LBB0_81
	s_waitcnt vmcnt(0)
	s_cmpk_gt_u32 s44, 0xff
	s_cbranch_scc1 .LBB0_88
	s_barrier

; #define PG8_STAGE(bufoff, gbase, voff) do { _Pragma("unroll") for (int _i = 0; _i < 2; ++_i) \
;         __builtin_amdgcn_global_load_lds((const unsigned*)((const char*)(gbase) + (voff)[_i]), (LAS unsigned*)(lds + (bufoff) + ldsw + _i * 8192), 16, 0, 0); } while (0)
; #define PG8_LDA(dst, b, h) do { _Pragma("unroll") for (int m = 0; m < 4; ++m) _Pragma("unroll") for (int k = 0; k < 2; ++k) dst[m][k] = *(const LAS h16x8*)(lds + PG8_SA(b, h) + aoff + m * 2048 + k * 1024); } while (0)
; #define PG8_LDB(dst, b, h) do { _Pragma("unroll") for (int n = 0; n < 2; ++n) _Pragma("unroll") for (int k = 0; k < 2; ++k) dst[n][k] = *(const LAS h16x8*)(lds + PG8_SB(b, h) + boff + n * 2048 + k * 1024); } while (0)
; #define PG8_MMA(ai, bj, At, Bt) do { __builtin_amdgcn_s_setprio(1); _Pragma("unroll") for (int m = 0; m < 4; ++m) _Pragma("unroll") for (int n = 0; n < 2; ++n) _Pragma("unroll") for (int k = 0; k < 2; ++k) \
;         acc[ai][bj][m][n] = __builtin_amdgcn_mfma_f32_16x16x32_f16(Bt[n][k], At[m][k], acc[ai][bj][m][n], 0, 0, 0); __builtin_amdgcn_s_setprio(0); } while (0)
; #define PG8_WAIT_V(n) asm volatile("s_waitcnt vmcnt(" #n ")" ::: "memory")
; #define PG8_WAIT_L(n) asm volatile("s_waitcnt lgkmcnt(" #n ")" ::: "memory")
; #define PG8_BAR __builtin_amdgcn_s_barrier()
; #define PG8_SCHED __builtin_amdgcn_sched_barrier(0)
; template <class Epi>
; __device__ __forceinline__ void gemm_phase(LAS unsigned char* lds, const Gemm g, const StaticOrder& S, const Epi& E) {
;     ...
;             PG8_LDB(B0, 0, 0); PG8_SCHED; PG8_LDA(At, 0, 0); PG8_STAGE(PG8_SA(1, 1), a1 + hstep, voffA);
;             PG8_WAIT_L(8); PG8_BAR; PG8_WAIT_L(0); PG8_MMA(0, 0, At, B0); PG8_BAR; PG8_SCHED;
;             PG8_LDB(B1, 0, 1); PG8_STAGE(PG8_SB(0, 0), b2, voffB);
;             PG8_BAR; PG8_WAIT_L(0); PG8_MMA(0, 1, At, B1); PG8_BAR;
;             PG8_LDA(At, 0, 1); PG8_STAGE(PG8_SA(0, 0), a2, voffA);
;             PG8_BAR; PG8_WAIT_L(0); PG8_MMA(1, 0, At, B0); PG8_BAR; PG8_SCHED;
;             PG8_STAGE(PG8_SB(0, 1), b2 + hstep, voffB);
;             PG8_WAIT_V(6); PG8_BAR; PG8_MMA(1, 1, At, B1); PG8_BAR;
;             PG8_LDB(B0, 1, 0); PG8_SCHED; PG8_LDA(At, 1, 0); PG8_STAGE(PG8_SA(0, 1), a2 + hstep, voffA);
;             PG8_WAIT_L(8); PG8_BAR; PG8_WAIT_L(0); PG8_MMA(0, 0, At, B0); PG8_BAR; PG8_SCHED;
.LBB0_483:
	ds_read_b128 v[160:163], v168
	ds_read_b128 v[164:167], v168 offset:1024
	ds_read_b128 v[172:175], v168 offset:2048
	ds_read_b128 v[176:179], v168 offset:3072
	s_add_u32 s36, s0, 0xfffc0080
	s_addc_u32 s37, s1, -1
	s_cmp_eq_u32 s63, 12
	s_cselect_b32 s39, s27, s37
	s_cselect_b32 s38, s59, s36
	s_cselect_b32 s37, s25, s62
	s_cselect_b32 s36, s60, s61
	v_lshl_add_u64 v[212:213], s[0:1], 0, v[152:153]
	s_add_i32 m0, s35, 0xc000
	ds_read_b128 v[180:183], v169
	ds_read_b128 v[184:187], v169 offset:1024
	ds_read_b128 v[188:191], v169 offset:2048
	ds_read_b128 v[192:195], v169 offset:3072
	ds_read_b128 v[196:199], v169 offset:4096
	ds_read_b128 v[200:203], v169 offset:5120
	ds_read_b128 v[204:207], v169 offset:6144
	ds_read_b128 v[208:211], v169 offset:7168
	global_load_lds_dwordx4 v[212:213], off
	v_lshl_add_u64 v[212:213], s[0:1], 0, v[154:155]
	s_add_i32 m0, s35, 0xe000
	s_nop 0
	global_load_lds_dwordx4 v[212:213], off
	s_waitcnt lgkmcnt(8)
	s_barrier
	s_waitcnt lgkmcnt(0)
	s_setprio 1
	s_waitcnt lgkmcnt(0)
	v_mfma_f32_16x16x32_f16 v[124:127], v[160:163], v[180:183], v[124:127]
	v_mfma_f32_16x16x32_f16 v[120:123], v[172:175], v[180:183], v[120:123]
	v_mfma_f32_16x16x32_f16 v[108:111], v[160:163], v[188:191], v[108:111]
	v_mfma_f32_16x16x32_f16 v[104:107], v[172:175], v[188:191], v[104:107]
	v_mfma_f32_16x16x32_f16 v[92:95], v[160:163], v[196:199], v[92:95]
	v_mfma_f32_16x16x32_f16 v[88:91], v[172:175], v[196:199], v[88:91]
	v_mfma_f32_16x16x32_f16 v[76:79], v[160:163], v[204:207], v[76:79]
	v_mfma_f32_16x16x32_f16 v[72:75], v[172:175], v[204:207], v[72:75]
	v_mfma_f32_16x16x32_f16 v[124:127], v[164:167], v[184:187], v[124:127]
	v_mfma_f32_16x16x32_f16 v[120:123], v[176:179], v[184:187], v[120:123]
	v_mfma_f32_16x16x32_f16 v[108:111], v[164:167], v[192:195], v[108:111]
	v_mfma_f32_16x16x32_f16 v[104:107], v[176:179], v[192:195], v[104:107]
	v_mfma_f32_16x16x32_f16 v[92:95], v[164:167], v[200:203], v[92:95]
	v_mfma_f32_16x16x32_f16 v[88:91], v[176:179], v[200:203], v[88:91]
	v_mfma_f32_16x16x32_f16 v[76:79], v[164:167], v[208:211], v[76:79]
	v_mfma_f32_16x16x32_f16 v[72:75], v[176:179], v[208:211], v[72:75]
	s_setprio 0
	s_barrier
	s_add_i32 s64, s51, s44
	v_lshl_add_u64 v[228:229], s[36:37], 0, v[144:145]
	s_mov_b32 m0, s64
	ds_read_b128 v[212:215], v170
	ds_read_b128 v[216:219], v170 offset:1024
	ds_read_b128 v[220:223], v170 offset:2048
	ds_read_b128 v[224:227], v170 offset:3072
	global_load_lds_dwordx4 v[228:229], off
	v_lshl_add_u64 v[230:231], s[36:37], 0, v[150:151]
	s_add_i32 m0, s64, 0x2000
	s_nop 0
	global_load_lds_dwordx4 v[230:231], off
	s_barrier
	s_waitcnt lgkmcnt(0)
	s_setprio 1
	s_waitcnt lgkmcnt(0)
	v_mfma_f32_16x16x32_f16 v[116:119], v[212:215], v[180:183], v[116:119]
	v_mfma_f32_16x16x32_f16 v[112:115], v[220:223], v[180:183], v[112:115]
	v_mfma_f32_16x16x32_f16 v[100:103], v[212:215], v[188:191], v[100:103]
	v_mfma_f32_16x16x32_f16 v[96:99], v[220:223], v[188:191], v[96:99]
	v_mfma_f32_16x16x32_f16 v[84:87], v[212:215], v[196:199], v[84:87]
	v_mfma_f32_16x16x32_f16 v[80:83], v[220:223], v[196:199], v[80:83]
	v_mfma_f32_16x16x32_f16 v[68:71], v[212:215], v[204:207], v[68:71]
	v_mfma_f32_16x16x32_f16 v[64:67], v[220:223], v[204:207], v[64:67]
	v_mfma_f32_16x16x32_f16 v[116:119], v[216:219], v[184:187], v[116:119]
	v_mfma_f32_16x16x32_f16 v[112:115], v[224:227], v[184:187], v[112:115]
	v_mfma_f32_16x16x32_f16 v[100:103], v[216:219], v[192:195], v[100:103]
	v_mfma_f32_16x16x32_f16 v[96:99], v[224:227], v[192:195], v[96:99]
	v_mfma_f32_16x16x32_f16 v[84:87], v[216:219], v[200:203], v[84:87]
	v_mfma_f32_16x16x32_f16 v[80:83], v[224:227], v[200:203], v[80:83]
	v_mfma_f32_16x16x32_f16 v[68:71], v[216:219], v[208:211], v[68:71]
	v_mfma_f32_16x16x32_f16 v[64:67], v[224:227], v[208:211], v[64:67]
	s_setprio 0
	s_mov_b32 m0, s35
	v_lshl_add_u64 v[232:233], s[38:39], 0, v[142:143]
	s_barrier
	ds_read_b128 v[180:183], v169 offset:16384
	ds_read_b128 v[184:187], v169 offset:17408
	ds_read_b128 v[188:191], v169 offset:18432
	ds_read_b128 v[192:195], v169 offset:19456
	ds_read_b128 v[196:199], v169 offset:20480
	ds_read_b128 v[200:203], v169 offset:21504
	ds_read_b128 v[204:207], v169 offset:22528
	ds_read_b128 v[208:211], v169 offset:23552
	global_load_lds_dwordx4 v[232:233], off
	v_lshl_add_u64 v[234:235], s[38:39], 0, v[148:149]
	s_mov_b32 m0, s45
	s_nop 0
	global_load_lds_dwordx4 v[234:235], off
	s_barrier
	s_waitcnt lgkmcnt(0)
	s_setprio 1
	s_waitcnt lgkmcnt(0)
	v_mfma_f32_16x16x32_f16 v[60:63], v[160:163], v[180:183], v[60:63]
	v_mfma_f32_16x16x32_f16 v[56:59], v[172:175], v[180:183], v[56:59]
	v_mfma_f32_16x16x32_f16 v[44:47], v[160:163], v[188:191], v[44:47]
	v_mfma_f32_16x16x32_f16 v[40:43], v[172:175], v[188:191], v[40:43]
	v_mfma_f32_16x16x32_f16 v[28:31], v[160:163], v[196:199], v[28:31]
	v_mfma_f32_16x16x32_f16 v[24:27], v[172:175], v[196:199], v[24:27]
	v_mfma_f32_16x16x32_f16 v[12:15], v[160:163], v[204:207], v[12:15]
	v_mfma_f32_16x16x32_f16 v[8:11], v[172:175], v[204:207], v[8:11]
	v_mfma_f32_16x16x32_f16 v[60:63], v[164:167], v[184:187], v[60:63]
	v_mfma_f32_16x16x32_f16 v[56:59], v[176:179], v[184:187], v[56:59]
	v_mfma_f32_16x16x32_f16 v[44:47], v[164:167], v[192:195], v[44:47]
	v_mfma_f32_16x16x32_f16 v[40:43], v[176:179], v[192:195], v[40:43]
	v_mfma_f32_16x16x32_f16 v[28:31], v[164:167], v[200:203], v[28:31]
	v_mfma_f32_16x16x32_f16 v[24:27], v[176:179], v[200:203], v[24:27]
	v_mfma_f32_16x16x32_f16 v[12:15], v[164:167], v[208:211], v[12:15]
	v_mfma_f32_16x16x32_f16 v[8:11], v[176:179], v[208:211], v[8:11]
	s_setprio 0
	s_barrier
; #define PG8_STAGE(bufoff, gbase, voff) do { _Pragma("unroll") for (int _i = 0; _i < 2; ++_i) \
;         __builtin_amdgcn_global_load_lds((const unsigned*)((const char*)(gbase) + (voff)[_i]), (LAS unsigned*)(lds + (bufoff) + ldsw + _i * 8192), 16, 0, 0); } while (0)
; #define PG8_LDA(dst, b, h) do { _Pragma("unroll") for (int m = 0; m < 4; ++m) _Pragma("unroll") for (int k = 0; k < 2; ++k) dst[m][k] = *(const LAS h16x8*)(lds + PG8_SA(b, h) + aoff + m * 2048 + k * 1024); } while (0)
; #define PG8_LDB(dst, b, h) do { _Pragma("unroll") for (int n = 0; n < 2; ++n) _Pragma("unroll") for (int k = 0; k < 2; ++k) dst[n][k] = *(const LAS h16x8*)(lds + PG8_SB(b, h) + boff + n * 2048 + k * 1024); } while (0)
; #define PG8_MMA(ai, bj, At, Bt) do { __builtin_amdgcn_s_setprio(1); _Pragma("unroll") for (int m = 0; m < 4; ++m) _Pragma("unroll") for (int n = 0; n < 2; ++n) _Pragma("unroll") for (int k = 0; k < 2; ++k) \
;         acc[ai][bj][m][n] = __builtin_amdgcn_mfma_f32_16x16x32_f16(Bt[n][k], At[m][k], acc[ai][bj][m][n], 0, 0, 0); __builtin_amdgcn_s_setprio(0); } while (0)
; #define PG8_WAIT_V(n) asm volatile("s_waitcnt vmcnt(" #n ")" ::: "memory")
; #define PG8_WAIT_L(n) asm volatile("s_waitcnt lgkmcnt(" #n ")" ::: "memory")
; #define PG8_BAR __builtin_amdgcn_s_barrier()
; #define PG8_SCHED __builtin_amdgcn_sched_barrier(0)
; template <class Epi>
; __device__ __forceinline__ void gemm_phase(LAS unsigned char* lds, const Gemm g, const StaticOrder& S, const Epi& E) {
;     ...
;             PG8_WAIT_V(6); PG8_BAR; PG8_MMA(1, 1, At, B1); PG8_BAR;
;             PG8_LDB(B0, 1, 0); PG8_SCHED; PG8_LDA(At, 1, 0); PG8_STAGE(PG8_SA(0, 1), a2 + hstep, voffA);
;             PG8_WAIT_L(8); PG8_BAR; PG8_WAIT_L(0); PG8_MMA(0, 0, At, B0); PG8_BAR; PG8_SCHED;
;             PG8_LDB(B1, 1, 1); PG8_STAGE(PG8_SB(1, 0), b3, voffB);
;             PG8_BAR; PG8_WAIT_L(0); PG8_MMA(0, 1, At, B1); PG8_BAR;
;             PG8_LDA(At, 1, 1); PG8_STAGE(PG8_SA(1, 0), a3, voffA);
;             PG8_BAR; PG8_WAIT_L(0); PG8_MMA(1, 0, At, B0); PG8_BAR; PG8_SCHED;
	s_add_u32 s64, s36, 0x40000
	s_addc_u32 s65, s37, 0
	s_add_i32 s66, s52, s44
	v_lshl_add_u64 v[160:161], s[64:65], 0, v[144:145]
	s_mov_b32 m0, s66
	s_nop 0
	global_load_lds_dwordx4 v[160:161], off
	v_lshl_add_u64 v[160:161], s[64:65], 0, v[150:151]
	s_add_i32 m0, s66, 0x2000
	s_nop 0
	global_load_lds_dwordx4 v[160:161], off
	s_waitcnt vmcnt(6)
	s_barrier
	s_setprio 1
	v_mfma_f32_16x16x32_f16 v[52:55], v[212:215], v[180:183], v[52:55]
	v_mfma_f32_16x16x32_f16 v[48:51], v[220:223], v[180:183], v[48:51]
	v_mfma_f32_16x16x32_f16 v[36:39], v[212:215], v[188:191], v[36:39]
	v_mfma_f32_16x16x32_f16 v[32:35], v[220:223], v[188:191], v[32:35]
	v_mfma_f32_16x16x32_f16 v[20:23], v[212:215], v[196:199], v[20:23]
	v_mfma_f32_16x16x32_f16 v[16:19], v[220:223], v[196:199], v[16:19]
	v_mfma_f32_16x16x32_f16 v[4:7], v[212:215], v[204:207], v[4:7]
	v_mfma_f32_16x16x32_f16 v[0:3], v[220:223], v[204:207], v[0:3]
	v_mfma_f32_16x16x32_f16 v[52:55], v[216:219], v[184:187], v[52:55]
	v_mfma_f32_16x16x32_f16 v[48:51], v[224:227], v[184:187], v[48:51]
	v_mfma_f32_16x16x32_f16 v[36:39], v[216:219], v[192:195], v[36:39]
	v_mfma_f32_16x16x32_f16 v[32:35], v[224:227], v[192:195], v[32:35]
	v_mfma_f32_16x16x32_f16 v[20:23], v[216:219], v[200:203], v[20:23]
	v_mfma_f32_16x16x32_f16 v[16:19], v[224:227], v[200:203], v[16:19]
	v_mfma_f32_16x16x32_f16 v[4:7], v[216:219], v[208:211], v[4:7]
	v_mfma_f32_16x16x32_f16 v[0:3], v[224:227], v[208:211], v[0:3]
	s_setprio 0
	s_add_i32 s64, 0, 0x18000
	v_add_u32_e32 v176, s64, v141
	s_barrier
	ds_read_b128 v[160:163], v176
	ds_read_b128 v[164:167], v176 offset:1024
	ds_read_b128 v[172:175], v176 offset:2048
	ds_read_b128 v[176:179], v176 offset:3072
	s_add_u32 s38, s38, 0x40000
	s_addc_u32 s39, s39, 0
	s_mov_b32 m0, s46
	v_lshl_add_u64 v[212:213], s[38:39], 0, v[142:143]
	ds_read_b128 v[180:183], v169 offset:32768
	ds_read_b128 v[184:187], v169 offset:33792
	ds_read_b128 v[188:191], v169 offset:34816
	ds_read_b128 v[192:195], v169 offset:35840
	ds_read_b128 v[196:199], v169 offset:36864
	ds_read_b128 v[200:203], v169 offset:37888
	ds_read_b128 v[204:207], v169 offset:38912
	ds_read_b128 v[208:211], v169 offset:39936
	global_load_lds_dwordx4 v[212:213], off
	v_lshl_add_u64 v[212:213], s[38:39], 0, v[148:149]
	s_mov_b32 m0, s47
	s_nop 0
	global_load_lds_dwordx4 v[212:213], off
	s_waitcnt lgkmcnt(8)
	s_barrier
	s_waitcnt lgkmcnt(0)
	s_setprio 1
	s_waitcnt lgkmcnt(0)
	v_mfma_f32_16x16x32_f16 v[124:127], v[160:163], v[180:183], v[124:127]
	v_mfma_f32_16x16x32_f16 v[120:123], v[172:175], v[180:183], v[120:123]
	v_mfma_f32_16x16x32_f16 v[108:111], v[160:163], v[188:191], v[108:111]
	v_mfma_f32_16x16x32_f16 v[104:107], v[172:175], v[188:191], v[104:107]
	v_mfma_f32_16x16x32_f16 v[92:95], v[160:163], v[196:199], v[92:95]
	v_mfma_f32_16x16x32_f16 v[88:91], v[172:175], v[196:199], v[88:91]
	v_mfma_f32_16x16x32_f16 v[76:79], v[160:163], v[204:207], v[76:79]
	v_mfma_f32_16x16x32_f16 v[72:75], v[172:175], v[204:207], v[72:75]
	v_mfma_f32_16x16x32_f16 v[124:127], v[164:167], v[184:187], v[124:127]
	v_mfma_f32_16x16x32_f16 v[120:123], v[176:179], v[184:187], v[120:123]
	v_mfma_f32_16x16x32_f16 v[108:111], v[164:167], v[192:195], v[108:111]
	v_mfma_f32_16x16x32_f16 v[104:107], v[176:179], v[192:195], v[104:107]
	v_mfma_f32_16x16x32_f16 v[92:95], v[164:167], v[200:203], v[92:95]
	v_mfma_f32_16x16x32_f16 v[88:91], v[176:179], v[200:203], v[88:91]
	v_mfma_f32_16x16x32_f16 v[76:79], v[164:167], v[208:211], v[76:79]
	v_mfma_f32_16x16x32_f16 v[72:75], v[176:179], v[208:211], v[72:75]
	s_setprio 0
	s_barrier
	s_add_i32 s38, 0, 0x1c000
	s_add_i32 s39, s64, s44
	v_add_u32_e32 v224, s38, v141
	v_lshl_add_u64 v[228:229], v[228:229], 0, s[8:9]
	s_mov_b32 m0, s39
	ds_read_b128 v[212:215], v224
	ds_read_b128 v[216:219], v224 offset:1024
	ds_read_b128 v[220:223], v224 offset:2048
	ds_read_b128 v[224:227], v224 offset:3072
	global_load_lds_dwordx4 v[228:229], off
	v_lshl_add_u64 v[228:229], v[230:231], 0, s[8:9]
	s_add_i32 m0, s39, 0x2000
	s_nop 0
	global_load_lds_dwordx4 v[228:229], off
	s_barrier
	s_waitcnt lgkmcnt(0)
	s_setprio 1
	s_waitcnt lgkmcnt(0)
	v_mfma_f32_16x16x32_f16 v[116:119], v[212:215], v[180:183], v[116:119]
	v_mfma_f32_16x16x32_f16 v[112:115], v[220:223], v[180:183], v[112:115]
	v_mfma_f32_16x16x32_f16 v[100:103], v[212:215], v[188:191], v[100:103]
	v_mfma_f32_16x16x32_f16 v[96:99], v[220:223], v[188:191], v[96:99]
	v_mfma_f32_16x16x32_f16 v[84:87], v[212:215], v[196:199], v[84:87]
	v_mfma_f32_16x16x32_f16 v[80:83], v[220:223], v[196:199], v[80:83]
	v_mfma_f32_16x16x32_f16 v[68:71], v[212:215], v[204:207], v[68:71]
	v_mfma_f32_16x16x32_f16 v[64:67], v[220:223], v[204:207], v[64:67]
	v_mfma_f32_16x16x32_f16 v[116:119], v[216:219], v[184:187], v[116:119]
	v_mfma_f32_16x16x32_f16 v[112:115], v[224:227], v[184:187], v[112:115]
	v_mfma_f32_16x16x32_f16 v[100:103], v[216:219], v[192:195], v[100:103]
	v_mfma_f32_16x16x32_f16 v[96:99], v[224:227], v[192:195], v[96:99]
	v_mfma_f32_16x16x32_f16 v[84:87], v[216:219], v[200:203], v[84:87]
	v_mfma_f32_16x16x32_f16 v[80:83], v[224:227], v[200:203], v[80:83]
	v_mfma_f32_16x16x32_f16 v[68:71], v[216:219], v[208:211], v[68:71]
	v_mfma_f32_16x16x32_f16 v[64:67], v[224:227], v[208:211], v[64:67]
	s_setprio 0
	s_mov_b32 m0, s49
	v_lshl_add_u64 v[228:229], v[232:233], 0, s[8:9]
	s_barrier
	ds_read_b128 v[180:183], v169 offset:49152
	ds_read_b128 v[184:187], v169 offset:50176
	ds_read_b128 v[188:191], v169 offset:51200
	ds_read_b128 v[192:195], v169 offset:52224
	ds_read_b128 v[196:199], v169 offset:53248
	ds_read_b128 v[200:203], v169 offset:54272
	ds_read_b128 v[204:207], v169 offset:55296
	ds_read_b128 v[208:211], v169 offset:56320
	global_load_lds_dwordx4 v[228:229], off
	v_lshl_add_u64 v[228:229], v[234:235], 0, s[8:9]
	s_mov_b32 m0, s50
	s_nop 0
	global_load_lds_dwordx4 v[228:229], off
	s_barrier
; #define PG8_WAIT_V(n) asm volatile("s_waitcnt vmcnt(" #n ")" ::: "memory")
; #define PG8_WAIT_L(n) asm volatile("s_waitcnt lgkmcnt(" #n ")" ::: "memory")
; #define PG8_BAR __builtin_amdgcn_s_barrier()
; #define PG8_SCHED __builtin_amdgcn_sched_barrier(0)
; template <class Epi>
; __device__ __forceinline__ void gemm_phase(LAS unsigned char* lds, const Gemm g, const StaticOrder& S, const Epi& E) {
;     ...
;             PG8_BAR; PG8_WAIT_L(0); PG8_MMA(1, 0, At, B0); PG8_BAR; PG8_SCHED;
;             PG8_STAGE(PG8_SB(1, 1), b3 + hstep, voffB);
;             PG8_WAIT_V(6); PG8_BAR; PG8_MMA(1, 1, At, B1); PG8_BAR;
;     __device__ __forceinline__ void operator()(const f32x4 (&acc)[2][2][4][2], const pg8::Unit& u, int wr, int wc, int fr, int fq) const {
;         const int row0 = u.pm * 256 + wr * 64 + fr, col0 = u.pn * 256 + wc * 32 + 8 * fq;
; #pragma unroll
;         for (int ai = 0; ai < 2; ++ai)
; #pragma unroll
;             for (int m = 0; m < 4; ++m) {
;                 const int row = row0 + ai * 128 + m * 16;
;                 float ss = 0.f, rstd = 1.f;
;                 if (MODE == 2) rstd = rsqrtf(rowss[row] * (1.f / 1024.f) + EPS);
; #pragma unroll
;                 for (int bj = 0; bj < 2; ++bj) {
;                     const int c = col0 + bj * 128;
;                     f32x4 v0 = acc[ai][bj][m][0], v1 = acc[ai][bj][m][1];
;                     if (MODE == 1) {
;                         const float* rp = res + (size_t)row * ldres + c;
;                         v0 += *(const f32x4*)rp; v1 += *(const f32x4*)(rp + 4);
;                     }
;                     if (MODE == 3) {
;                         const h16x8 r8 = *(const h16x8*)(res16 + (size_t)row * ldres + c);
; #pragma unroll
;                         for (int j = 0; j < 4; ++j) { v0[j] += (float)r8[j]; v1[j] += (float)r8[4 + j]; }
;                     }
;                     if (MODE == 1 || MODE == 3) {
;                         ss += v0[0] * v0[0] + v0[1] * v0[1] + v0[2] * v0[2] + v0[3] * v0[3] + v1[0] * v1[0] + v1[1] * v1[1] + v1[2] * v1[2] + v1[3] * v1[3];
;                     }
;                     if (MODE == 2) {
; #pragma unroll
;                         for (int j = 0; j < 4; ++j) { float a = fmaxf(v0[j] * rstd, 0.f), b = fmaxf(v1[j] * rstd, 0.f); v0[j] = a * a; v1[j] = b * b; }
;                     }
;                     *(h16x8*)(o16 + (size_t)row * ld16 + c) = pack8(v0, v1);
	s_waitcnt lgkmcnt(0)
	s_setprio 1
	s_waitcnt lgkmcnt(0)
	v_mfma_f32_16x16x32_f16 v[60:63], v[160:163], v[180:183], v[60:63]
	v_mfma_f32_16x16x32_f16 v[56:59], v[172:175], v[180:183], v[56:59]
	v_mfma_f32_16x16x32_f16 v[44:47], v[160:163], v[188:191], v[44:47]
	v_mfma_f32_16x16x32_f16 v[40:43], v[172:175], v[188:191], v[40:43]
	v_mfma_f32_16x16x32_f16 v[28:31], v[160:163], v[196:199], v[28:31]
	v_mfma_f32_16x16x32_f16 v[24:27], v[172:175], v[196:199], v[24:27]
	v_mfma_f32_16x16x32_f16 v[12:15], v[160:163], v[204:207], v[12:15]
	v_mfma_f32_16x16x32_f16 v[8:11], v[172:175], v[204:207], v[8:11]
	v_mfma_f32_16x16x32_f16 v[60:63], v[164:167], v[184:187], v[60:63]
	v_mfma_f32_16x16x32_f16 v[56:59], v[176:179], v[184:187], v[56:59]
	v_mfma_f32_16x16x32_f16 v[44:47], v[164:167], v[192:195], v[44:47]
	v_mfma_f32_16x16x32_f16 v[40:43], v[176:179], v[192:195], v[40:43]
	v_mfma_f32_16x16x32_f16 v[28:31], v[164:167], v[200:203], v[28:31]
	v_mfma_f32_16x16x32_f16 v[24:27], v[176:179], v[200:203], v[24:27]
	v_mfma_f32_16x16x32_f16 v[12:15], v[164:167], v[208:211], v[12:15]
	v_mfma_f32_16x16x32_f16 v[8:11], v[176:179], v[208:211], v[8:11]
	s_setprio 0
	s_barrier
	s_add_u32 s36, s36, 0x40080
	s_addc_u32 s37, s37, 0
	s_add_i32 s38, s38, s44
	v_lshl_add_u64 v[160:161], s[36:37], 0, v[144:145]
	s_mov_b32 m0, s38
	s_nop 0
	global_load_lds_dwordx4 v[160:161], off
	v_lshl_add_u64 v[160:161], s[36:37], 0, v[150:151]
	s_add_i32 m0, s38, 0x2000
	s_nop 0
	global_load_lds_dwordx4 v[160:161], off
	s_waitcnt vmcnt(6)
	s_barrier
	s_setprio 1
	v_mfma_f32_16x16x32_f16 v[52:55], v[212:215], v[180:183], v[52:55]
	v_mfma_f32_16x16x32_f16 v[48:51], v[220:223], v[180:183], v[48:51]
	v_mfma_f32_16x16x32_f16 v[36:39], v[212:215], v[188:191], v[36:39]
	v_mfma_f32_16x16x32_f16 v[32:35], v[220:223], v[188:191], v[32:35]
	v_mfma_f32_16x16x32_f16 v[20:23], v[212:215], v[196:199], v[20:23]
	v_mfma_f32_16x16x32_f16 v[16:19], v[220:223], v[196:199], v[16:19]
	v_mfma_f32_16x16x32_f16 v[4:7], v[212:215], v[204:207], v[4:7]
	v_mfma_f32_16x16x32_f16 v[0:3], v[220:223], v[204:207], v[0:3]
	v_mfma_f32_16x16x32_f16 v[52:55], v[216:219], v[184:187], v[52:55]
	v_mfma_f32_16x16x32_f16 v[48:51], v[224:227], v[184:187], v[48:51]
	v_mfma_f32_16x16x32_f16 v[36:39], v[216:219], v[192:195], v[36:39]
	v_mfma_f32_16x16x32_f16 v[32:35], v[224:227], v[192:195], v[32:35]
	v_mfma_f32_16x16x32_f16 v[20:23], v[216:219], v[200:203], v[20:23]
	v_mfma_f32_16x16x32_f16 v[16:19], v[224:227], v[200:203], v[16:19]
	v_mfma_f32_16x16x32_f16 v[4:7], v[216:219], v[208:211], v[4:7]
	v_mfma_f32_16x16x32_f16 v[0:3], v[224:227], v[208:211], v[0:3]
	s_setprio 0
	s_add_i32 s63, s63, 2
	s_add_u32 s0, s0, 0x100
	s_addc_u32 s1, s1, 0
	s_add_u32 s61, s61, 0x100
	s_addc_u32 s62, s62, 0
	s_cmp_gt_u32 s63, 13
	s_barrier
	s_cbranch_scc0 .LBB0_483
	v_lshl_add_u32 v166, s34, 8, v139
	v_ashrrev_i32_e32 v167, 31, v166
	v_lshl_add_u64 v[160:161], v[166:167], 2, s[14:15]
	global_load_dword v176, v[160:161], off
	global_load_dword v182, v[160:161], off offset:64
	global_load_dword v183, v[160:161], off offset:128
	global_load_dword v184, v[160:161], off offset:192
	global_load_dword v185, v[160:161], off offset:512
	global_load_dword v186, v[160:161], off offset:576
	global_load_dword v187, v[160:161], off offset:640
	global_load_dword v188, v[160:161], off offset:704
	v_lshl_or_b32 v162, s58, 8, v147
	v_and_b32_e32 v164, 0x60, v147
	v_add_lshl_u32 v162, v162, v164, 1
	v_mov_b32_e32 v163, 0
	v_lshlrev_b64 v[174:175], 13, v[166:167]
	v_lshl_add_u64 v[164:165], s[12:13], 0, v[174:175]
	v_lshl_add_u64 v[164:165], v[164:165], 0, v[162:163]
	s_mov_b32 s58, s24
	s_mov_b32 s34, s26
	s_mov_b64 s[36:37], s[30:31]
	s_mov_b64 s[38:39], s[28:29]
	v_and_b32_e32 v212, 8, v139
	v_cmp_eq_u32_e64 s[98:99], 0, v212
	v_mov_b32_e32 v212, 0xffff0040
	v_cndmask_b32_e64 v214, v212, 0, s[98:99]
	v_cndmask_b32_e64 v215, -1, 0, s[98:99]
	v_mov_b32_e32 v212, 0x10040
	v_cndmask_b32_e64 v216, 0, v212, s[98:99]
	v_mov_b32_e32 v217, 0
	v_mov_b32_e32 v213, 0x358637bd
	s_waitcnt vmcnt(0)
	v_fmamk_f32 v190, v176, 0x3a800000, v213
	v_mul_f32_e32 v191, 0x4b800000, v190
	v_cmp_gt_f32_e64 s[100:101], s53, v190
	s_nop 1
	v_cndmask_b32_e64 v190, v190, v191, s[100:101]
	v_rsq_f32_e32 v190, v190
	s_nop 0
	v_mul_f32_e32 v191, 0x45800000, v190
	v_cndmask_b32_e64 v190, v190, v191, s[100:101]
	v_pk_mul_f32 v[124:125], v[124:125], v[190:191] op_sel_hi:[1,0]
	v_pk_mul_f32 v[126:127], v[126:127], v[190:191] op_sel_hi:[1,0]
	v_pk_mul_f32 v[120:121], v[120:121], v[190:191] op_sel_hi:[1,0]
	v_pk_mul_f32 v[122:123], v[122:123], v[190:191] op_sel_hi:[1,0]
	v_max_f32_e32 v124, 0, v124
	v_max_f32_e32 v125, 0, v125
	v_max_f32_e32 v126, 0, v126
	v_max_f32_e32 v127, 0, v127
	v_max_f32_e32 v120, 0, v120
	v_max_f32_e32 v121, 0, v121
	v_max_f32_e32 v122, 0, v122
	v_max_f32_e32 v123, 0, v123
	v_pk_mul_f32 v[124:125], v[124:125], v[124:125]
	v_pk_mul_f32 v[126:127], v[126:127], v[126:127]
	v_pk_mul_f32 v[120:121], v[120:121], v[120:121]
	v_pk_mul_f32 v[122:123], v[122:123], v[122:123]
	v_cvt_pk_f16_f32 v124, v124, v125
	v_cvt_pk_f16_f32 v125, v126, v127
	v_cvt_pk_f16_f32 v126, v120, v121
	v_cvt_pk_f16_f32 v127, v122, v123
	v_pk_mul_f32 v[116:117], v[116:117], v[190:191] op_sel_hi:[1,0]
	v_pk_mul_f32 v[118:119], v[118:119], v[190:191] op_sel_hi:[1,0]
	v_pk_mul_f32 v[112:113], v[112:113], v[190:191] op_sel_hi:[1,0]
	v_pk_mul_f32 v[114:115], v[114:115], v[190:191] op_sel_hi:[1,0]
	v_max_f32_e32 v116, 0, v116
	v_max_f32_e32 v117, 0, v117
	v_max_f32_e32 v118, 0, v118
	v_max_f32_e32 v119, 0, v119
	v_max_f32_e32 v112, 0, v112
	v_max_f32_e32 v113, 0, v113
	v_max_f32_e32 v114, 0, v114
	v_max_f32_e32 v115, 0, v115
;     __device__ __forceinline__ void operator()(const f32x4 (&acc)[2][2][4][2], const pg8::Unit& u, int wr, int wc, int fr, int fq) const {
;     ...
;                 const int row = row0 + ai * 128 + m * 16;
;                 float ss = 0.f, rstd = 1.f;
;                 if (MODE == 2) rstd = rsqrtf(rowss[row] * (1.f / 1024.f) + EPS);
; #pragma unroll
;                 for (int bj = 0; bj < 2; ++bj) {
;                     const int c = col0 + bj * 128;
;                     f32x4 v0 = acc[ai][bj][m][0], v1 = acc[ai][bj][m][1];
;                     if (MODE == 1) {
;                         const float* rp = res + (size_t)row * ldres + c;
;                         v0 += *(const f32x4*)rp; v1 += *(const f32x4*)(rp + 4);
;                     }
;                     if (MODE == 3) {
;                         const h16x8 r8 = *(const h16x8*)(res16 + (size_t)row * ldres + c);
; #pragma unroll
;                         for (int j = 0; j < 4; ++j) { v0[j] += (float)r8[j]; v1[j] += (float)r8[4 + j]; }
;                     }
;                     if (MODE == 1 || MODE == 3) {
;                         ss += v0[0] * v0[0] + v0[1] * v0[1] + v0[2] * v0[2] + v0[3] * v0[3] + v1[0] * v1[0] + v1[1] * v1[1] + v1[2] * v1[2] + v1[3] * v1[3];
;                     }
;                     if (MODE == 2) {
; #pragma unroll
;                         for (int j = 0; j < 4; ++j) { float a = fmaxf(v0[j] * rstd, 0.f), b = fmaxf(v1[j] * rstd, 0.f); v0[j] = a * a; v1[j] = b * b; }
;                     }
;                     *(h16x8*)(o16 + (size_t)row * ld16 + c) = pack8(v0, v1);
	v_pk_mul_f32 v[116:117], v[116:117], v[116:117]
	v_pk_mul_f32 v[118:119], v[118:119], v[118:119]
	v_pk_mul_f32 v[112:113], v[112:113], v[112:113]
	v_pk_mul_f32 v[114:115], v[114:115], v[114:115]
	v_cvt_pk_f16_f32 v116, v116, v117
	v_cvt_pk_f16_f32 v117, v118, v119
	v_cvt_pk_f16_f32 v118, v112, v113
	v_cvt_pk_f16_f32 v119, v114, v115
	s_nop 1
	v_mov_b32_dpp v192, v116 row_ror:8 row_mask:0xf bank_mask:0xf
	v_mov_b32_dpp v193, v117 row_ror:8 row_mask:0xf bank_mask:0xf
	v_mov_b32_dpp v194, v118 row_ror:8 row_mask:0xf bank_mask:0xf
	v_mov_b32_dpp v195, v119 row_ror:8 row_mask:0xf bank_mask:0xf
	v_cndmask_b32_e64 v116, v192, v124, s[98:99]
	v_cndmask_b32_e64 v117, v193, v125, s[98:99]
	v_cndmask_b32_e64 v118, v194, v126, s[98:99]
	v_cndmask_b32_e64 v119, v195, v127, s[98:99]
	v_cndmask_b32_e64 v192, v124, v192, s[98:99]
	v_cndmask_b32_e64 v193, v125, v193, s[98:99]
	v_cndmask_b32_e64 v194, v126, v194, s[98:99]
	v_cndmask_b32_e64 v195, v127, v195, s[98:99]
	v_lshl_add_u64 v[196:197], v[164:165], 0, v[214:215]
	v_lshl_add_u64 v[198:199], v[164:165], 0, v[216:217]
	global_store_dwordx4 v[196:197], v[116:119], off sc0 sc1 nt
	global_store_dwordx4 v[198:199], v[192:195], off sc0 sc1 nt
	s_mov_b32 s100, 0x20000
	s_mov_b32 s101, 0
	v_lshl_add_u64 v[164:165], v[164:165], 0, s[100:101]
	v_fmamk_f32 v190, v182, 0x3a800000, v213
	v_mul_f32_e32 v191, 0x4b800000, v190
	v_cmp_gt_f32_e64 s[100:101], s53, v190
	s_nop 1
	v_cndmask_b32_e64 v190, v190, v191, s[100:101]
	v_rsq_f32_e32 v190, v190
	s_nop 0
	v_mul_f32_e32 v191, 0x45800000, v190
	v_cndmask_b32_e64 v190, v190, v191, s[100:101]
	v_pk_mul_f32 v[108:109], v[108:109], v[190:191] op_sel_hi:[1,0]
	v_pk_mul_f32 v[110:111], v[110:111], v[190:191] op_sel_hi:[1,0]
	v_pk_mul_f32 v[104:105], v[104:105], v[190:191] op_sel_hi:[1,0]
	v_pk_mul_f32 v[106:107], v[106:107], v[190:191] op_sel_hi:[1,0]
	v_max_f32_e32 v108, 0, v108
	v_max_f32_e32 v109, 0, v109
	v_max_f32_e32 v110, 0, v110
	v_max_f32_e32 v111, 0, v111
	v_max_f32_e32 v104, 0, v104
	v_max_f32_e32 v105, 0, v105
	v_max_f32_e32 v106, 0, v106
	v_max_f32_e32 v107, 0, v107
	v_pk_mul_f32 v[108:109], v[108:109], v[108:109]
	v_pk_mul_f32 v[110:111], v[110:111], v[110:111]
	v_pk_mul_f32 v[104:105], v[104:105], v[104:105]
	v_pk_mul_f32 v[106:107], v[106:107], v[106:107]
	v_cvt_pk_f16_f32 v108, v108, v109
	v_cvt_pk_f16_f32 v109, v110, v111
	v_cvt_pk_f16_f32 v110, v104, v105
	v_cvt_pk_f16_f32 v111, v106, v107
	v_pk_mul_f32 v[100:101], v[100:101], v[190:191] op_sel_hi:[1,0]
	v_pk_mul_f32 v[102:103], v[102:103], v[190:191] op_sel_hi:[1,0]
	v_pk_mul_f32 v[96:97], v[96:97], v[190:191] op_sel_hi:[1,0]
	v_pk_mul_f32 v[98:99], v[98:99], v[190:191] op_sel_hi:[1,0]
	v_max_f32_e32 v100, 0, v100
	v_max_f32_e32 v101, 0, v101
	v_max_f32_e32 v102, 0, v102
	v_max_f32_e32 v103, 0, v103
	v_max_f32_e32 v96, 0, v96
	v_max_f32_e32 v97, 0, v97
	v_max_f32_e32 v98, 0, v98
	v_max_f32_e32 v99, 0, v99
	v_pk_mul_f32 v[100:101], v[100:101], v[100:101]
	v_pk_mul_f32 v[102:103], v[102:103], v[102:103]
	v_pk_mul_f32 v[96:97], v[96:97], v[96:97]
	v_pk_mul_f32 v[98:99], v[98:99], v[98:99]
	v_cvt_pk_f16_f32 v100, v100, v101
	v_cvt_pk_f16_f32 v101, v102, v103
	v_cvt_pk_f16_f32 v102, v96, v97
	v_cvt_pk_f16_f32 v103, v98, v99
	s_nop 1
	v_mov_b32_dpp v204, v100 row_ror:8 row_mask:0xf bank_mask:0xf
	v_mov_b32_dpp v205, v101 row_ror:8 row_mask:0xf bank_mask:0xf
	v_mov_b32_dpp v206, v102 row_ror:8 row_mask:0xf bank_mask:0xf
	v_mov_b32_dpp v207, v103 row_ror:8 row_mask:0xf bank_mask:0xf
	v_cndmask_b32_e64 v100, v204, v108, s[98:99]
	v_cndmask_b32_e64 v101, v205, v109, s[98:99]
	v_cndmask_b32_e64 v102, v206, v110, s[98:99]
	v_cndmask_b32_e64 v103, v207, v111, s[98:99]
	v_cndmask_b32_e64 v204, v108, v204, s[98:99]
	v_cndmask_b32_e64 v205, v109, v205, s[98:99]
	v_cndmask_b32_e64 v206, v110, v206, s[98:99]
	v_cndmask_b32_e64 v207, v111, v207, s[98:99]
	v_lshl_add_u64 v[208:209], v[164:165], 0, v[214:215]
	v_lshl_add_u64 v[210:211], v[164:165], 0, v[216:217]
	global_store_dwordx4 v[208:209], v[100:103], off sc0 sc1 nt
	global_store_dwordx4 v[210:211], v[204:207], off sc0 sc1 nt
	s_mov_b32 s100, 0x20000
	s_mov_b32 s101, 0
	v_lshl_add_u64 v[164:165], v[164:165], 0, s[100:101]
	v_fmamk_f32 v190, v183, 0x3a800000, v213
	v_mul_f32_e32 v191, 0x4b800000, v190
	v_cmp_gt_f32_e64 s[100:101], s53, v190
	s_nop 1
	v_cndmask_b32_e64 v190, v190, v191, s[100:101]
	v_rsq_f32_e32 v190, v190
	s_nop 0
	v_mul_f32_e32 v191, 0x45800000, v190
	v_cndmask_b32_e64 v190, v190, v191, s[100:101]
	v_pk_mul_f32 v[92:93], v[92:93], v[190:191] op_sel_hi:[1,0]
	v_pk_mul_f32 v[94:95], v[94:95], v[190:191] op_sel_hi:[1,0]
	v_pk_mul_f32 v[88:89], v[88:89], v[190:191] op_sel_hi:[1,0]
	v_pk_mul_f32 v[90:91], v[90:91], v[190:191] op_sel_hi:[1,0]
	v_max_f32_e32 v92, 0, v92
	v_max_f32_e32 v93, 0, v93
	v_max_f32_e32 v94, 0, v94
	v_max_f32_e32 v95, 0, v95
	v_max_f32_e32 v88, 0, v88
	v_max_f32_e32 v89, 0, v89
	v_max_f32_e32 v90, 0, v90
	v_max_f32_e32 v91, 0, v91
	v_pk_mul_f32 v[92:93], v[92:93], v[92:93]
	v_pk_mul_f32 v[94:95], v[94:95], v[94:95]
	v_pk_mul_f32 v[88:89], v[88:89], v[88:89]
	v_pk_mul_f32 v[90:91], v[90:91], v[90:91]
	v_cvt_pk_f16_f32 v92, v92, v93
	v_cvt_pk_f16_f32 v93, v94, v95
	v_cvt_pk_f16_f32 v94, v88, v89
	v_cvt_pk_f16_f32 v95, v90, v91
	v_pk_mul_f32 v[84:85], v[84:85], v[190:191] op_sel_hi:[1,0]
	v_pk_mul_f32 v[86:87], v[86:87], v[190:191] op_sel_hi:[1,0]
	v_pk_mul_f32 v[80:81], v[80:81], v[190:191] op_sel_hi:[1,0]
	v_pk_mul_f32 v[82:83], v[82:83], v[190:191] op_sel_hi:[1,0]
	v_max_f32_e32 v84, 0, v84
	v_max_f32_e32 v85, 0, v85
	v_max_f32_e32 v86, 0, v86
	v_max_f32_e32 v87, 0, v87
	v_max_f32_e32 v80, 0, v80
	v_max_f32_e32 v81, 0, v81
;     __device__ __forceinline__ void operator()(const f32x4 (&acc)[2][2][4][2], const pg8::Unit& u, int wr, int wc, int fr, int fq) const {
;     ...
;                 const int row = row0 + ai * 128 + m * 16;
;                 float ss = 0.f, rstd = 1.f;
;                 if (MODE == 2) rstd = rsqrtf(rowss[row] * (1.f / 1024.f) + EPS);
; #pragma unroll
;                 for (int bj = 0; bj < 2; ++bj) {
;                     const int c = col0 + bj * 128;
;                     f32x4 v0 = acc[ai][bj][m][0], v1 = acc[ai][bj][m][1];
;                     if (MODE == 1) {
;                         const float* rp = res + (size_t)row * ldres + c;
;                         v0 += *(const f32x4*)rp; v1 += *(const f32x4*)(rp + 4);
;                     }
;                     if (MODE == 3) {
;                         const h16x8 r8 = *(const h16x8*)(res16 + (size_t)row * ldres + c);
; #pragma unroll
;                         for (int j = 0; j < 4; ++j) { v0[j] += (float)r8[j]; v1[j] += (float)r8[4 + j]; }
;                     }
;                     if (MODE == 1 || MODE == 3) {
;                         ss += v0[0] * v0[0] + v0[1] * v0[1] + v0[2] * v0[2] + v0[3] * v0[3] + v1[0] * v1[0] + v1[1] * v1[1] + v1[2] * v1[2] + v1[3] * v1[3];
;                     }
;                     if (MODE == 2) {
; #pragma unroll
;                         for (int j = 0; j < 4; ++j) { float a = fmaxf(v0[j] * rstd, 0.f), b = fmaxf(v1[j] * rstd, 0.f); v0[j] = a * a; v1[j] = b * b; }
;                     }
;                     *(h16x8*)(o16 + (size_t)row * ld16 + c) = pack8(v0, v1);
	v_max_f32_e32 v82, 0, v82
	v_max_f32_e32 v83, 0, v83
	v_pk_mul_f32 v[84:85], v[84:85], v[84:85]
	v_pk_mul_f32 v[86:87], v[86:87], v[86:87]
	v_pk_mul_f32 v[80:81], v[80:81], v[80:81]
	v_pk_mul_f32 v[82:83], v[82:83], v[82:83]
	v_cvt_pk_f16_f32 v84, v84, v85
	v_cvt_pk_f16_f32 v85, v86, v87
	v_cvt_pk_f16_f32 v86, v80, v81
	v_cvt_pk_f16_f32 v87, v82, v83
	s_nop 1
	v_mov_b32_dpp v192, v84 row_ror:8 row_mask:0xf bank_mask:0xf
	v_mov_b32_dpp v193, v85 row_ror:8 row_mask:0xf bank_mask:0xf
	v_mov_b32_dpp v194, v86 row_ror:8 row_mask:0xf bank_mask:0xf
	v_mov_b32_dpp v195, v87 row_ror:8 row_mask:0xf bank_mask:0xf
	v_cndmask_b32_e64 v84, v192, v92, s[98:99]
	v_cndmask_b32_e64 v85, v193, v93, s[98:99]
	v_cndmask_b32_e64 v86, v194, v94, s[98:99]
	v_cndmask_b32_e64 v87, v195, v95, s[98:99]
	v_cndmask_b32_e64 v192, v92, v192, s[98:99]
	v_cndmask_b32_e64 v193, v93, v193, s[98:99]
	v_cndmask_b32_e64 v194, v94, v194, s[98:99]
	v_cndmask_b32_e64 v195, v95, v195, s[98:99]
	v_lshl_add_u64 v[196:197], v[164:165], 0, v[214:215]
	v_lshl_add_u64 v[198:199], v[164:165], 0, v[216:217]
	global_store_dwordx4 v[196:197], v[84:87], off sc0 sc1 nt
	global_store_dwordx4 v[198:199], v[192:195], off sc0 sc1 nt
	s_mov_b32 s100, 0x20000
	s_mov_b32 s101, 0
	v_lshl_add_u64 v[164:165], v[164:165], 0, s[100:101]
	v_fmamk_f32 v190, v184, 0x3a800000, v213
	v_mul_f32_e32 v191, 0x4b800000, v190
	v_cmp_gt_f32_e64 s[100:101], s53, v190
	s_nop 1
	v_cndmask_b32_e64 v190, v190, v191, s[100:101]
	v_rsq_f32_e32 v190, v190
	s_nop 0
	v_mul_f32_e32 v191, 0x45800000, v190
	v_cndmask_b32_e64 v190, v190, v191, s[100:101]
	v_pk_mul_f32 v[76:77], v[76:77], v[190:191] op_sel_hi:[1,0]
	v_pk_mul_f32 v[78:79], v[78:79], v[190:191] op_sel_hi:[1,0]
	v_pk_mul_f32 v[72:73], v[72:73], v[190:191] op_sel_hi:[1,0]
	v_pk_mul_f32 v[74:75], v[74:75], v[190:191] op_sel_hi:[1,0]
	v_max_f32_e32 v76, 0, v76
	v_max_f32_e32 v77, 0, v77
	v_max_f32_e32 v78, 0, v78
	v_max_f32_e32 v79, 0, v79
	v_max_f32_e32 v72, 0, v72
	v_max_f32_e32 v73, 0, v73
	v_max_f32_e32 v74, 0, v74
	v_max_f32_e32 v75, 0, v75
	v_pk_mul_f32 v[76:77], v[76:77], v[76:77]
	v_pk_mul_f32 v[78:79], v[78:79], v[78:79]
	v_pk_mul_f32 v[72:73], v[72:73], v[72:73]
	v_pk_mul_f32 v[74:75], v[74:75], v[74:75]
	v_cvt_pk_f16_f32 v76, v76, v77
	v_cvt_pk_f16_f32 v77, v78, v79
	v_cvt_pk_f16_f32 v78, v72, v73
	v_cvt_pk_f16_f32 v79, v74, v75
	v_pk_mul_f32 v[68:69], v[68:69], v[190:191] op_sel_hi:[1,0]
	v_pk_mul_f32 v[70:71], v[70:71], v[190:191] op_sel_hi:[1,0]
	v_pk_mul_f32 v[64:65], v[64:65], v[190:191] op_sel_hi:[1,0]
	v_pk_mul_f32 v[66:67], v[66:67], v[190:191] op_sel_hi:[1,0]
	v_max_f32_e32 v68, 0, v68
	v_max_f32_e32 v69, 0, v69
	v_max_f32_e32 v70, 0, v70
	v_max_f32_e32 v71, 0, v71
	v_max_f32_e32 v64, 0, v64
	v_max_f32_e32 v65, 0, v65
	v_max_f32_e32 v66, 0, v66
	v_max_f32_e32 v67, 0, v67
	v_pk_mul_f32 v[68:69], v[68:69], v[68:69]
	v_pk_mul_f32 v[70:71], v[70:71], v[70:71]
	v_pk_mul_f32 v[64:65], v[64:65], v[64:65]
	v_pk_mul_f32 v[66:67], v[66:67], v[66:67]
	v_cvt_pk_f16_f32 v68, v68, v69
	v_cvt_pk_f16_f32 v69, v70, v71
	v_cvt_pk_f16_f32 v70, v64, v65
	v_cvt_pk_f16_f32 v71, v66, v67
	s_nop 1
	v_mov_b32_dpp v204, v68 row_ror:8 row_mask:0xf bank_mask:0xf
	v_mov_b32_dpp v205, v69 row_ror:8 row_mask:0xf bank_mask:0xf
	v_mov_b32_dpp v206, v70 row_ror:8 row_mask:0xf bank_mask:0xf
	v_mov_b32_dpp v207, v71 row_ror:8 row_mask:0xf bank_mask:0xf
	v_cndmask_b32_e64 v68, v204, v76, s[98:99]
	v_cndmask_b32_e64 v69, v205, v77, s[98:99]
	v_cndmask_b32_e64 v70, v206, v78, s[98:99]
	v_cndmask_b32_e64 v71, v207, v79, s[98:99]
	v_cndmask_b32_e64 v204, v76, v204, s[98:99]
	v_cndmask_b32_e64 v205, v77, v205, s[98:99]
	v_cndmask_b32_e64 v206, v78, v206, s[98:99]
	v_cndmask_b32_e64 v207, v79, v207, s[98:99]
	v_lshl_add_u64 v[208:209], v[164:165], 0, v[214:215]
	v_lshl_add_u64 v[210:211], v[164:165], 0, v[216:217]
	global_store_dwordx4 v[208:209], v[68:71], off sc0 sc1 nt
	global_store_dwordx4 v[210:211], v[204:207], off sc0 sc1 nt
	s_mov_b32 s100, 0xa0000
	s_mov_b32 s101, 0
	v_lshl_add_u64 v[164:165], v[164:165], 0, s[100:101]
	v_fmamk_f32 v190, v185, 0x3a800000, v213
	v_mul_f32_e32 v191, 0x4b800000, v190
	v_cmp_gt_f32_e64 s[100:101], s53, v190
	s_nop 1
	v_cndmask_b32_e64 v190, v190, v191, s[100:101]
	v_rsq_f32_e32 v190, v190
	s_nop 0
	v_mul_f32_e32 v191, 0x45800000, v190
	v_cndmask_b32_e64 v190, v190, v191, s[100:101]
	v_pk_mul_f32 v[60:61], v[60:61], v[190:191] op_sel_hi:[1,0]
	v_pk_mul_f32 v[62:63], v[62:63], v[190:191] op_sel_hi:[1,0]
	v_pk_mul_f32 v[56:57], v[56:57], v[190:191] op_sel_hi:[1,0]
	v_pk_mul_f32 v[58:59], v[58:59], v[190:191] op_sel_hi:[1,0]
	v_max_f32_e32 v60, 0, v60
	v_max_f32_e32 v61, 0, v61
	v_max_f32_e32 v62, 0, v62
	v_max_f32_e32 v63, 0, v63
	v_max_f32_e32 v56, 0, v56
	v_max_f32_e32 v57, 0, v57
	v_max_f32_e32 v58, 0, v58
	v_max_f32_e32 v59, 0, v59
	v_pk_mul_f32 v[60:61], v[60:61], v[60:61]
	v_pk_mul_f32 v[62:63], v[62:63], v[62:63]
	v_pk_mul_f32 v[56:57], v[56:57], v[56:57]
	v_pk_mul_f32 v[58:59], v[58:59], v[58:59]
	v_cvt_pk_f16_f32 v60, v60, v61
	v_cvt_pk_f16_f32 v61, v62, v63
	v_cvt_pk_f16_f32 v62, v56, v57
	v_cvt_pk_f16_f32 v63, v58, v59
	v_pk_mul_f32 v[52:53], v[52:53], v[190:191] op_sel_hi:[1,0]
	v_pk_mul_f32 v[54:55], v[54:55], v[190:191] op_sel_hi:[1,0]
	v_pk_mul_f32 v[48:49], v[48:49], v[190:191] op_sel_hi:[1,0]
	v_pk_mul_f32 v[50:51], v[50:51], v[190:191] op_sel_hi:[1,0]
	v_max_f32_e32 v52, 0, v52
	v_max_f32_e32 v53, 0, v53
	v_max_f32_e32 v54, 0, v54
	v_max_f32_e32 v55, 0, v55
	v_max_f32_e32 v48, 0, v48
	v_max_f32_e32 v49, 0, v49
	v_max_f32_e32 v50, 0, v50
	v_max_f32_e32 v51, 0, v51
	v_pk_mul_f32 v[52:53], v[52:53], v[52:53]
	v_pk_mul_f32 v[54:55], v[54:55], v[54:55]
;     __device__ __forceinline__ void operator()(const f32x4 (&acc)[2][2][4][2], const pg8::Unit& u, int wr, int wc, int fr, int fq) const {
;     ...
;                 const int row = row0 + ai * 128 + m * 16;
;                 float ss = 0.f, rstd = 1.f;
;                 if (MODE == 2) rstd = rsqrtf(rowss[row] * (1.f / 1024.f) + EPS);
; #pragma unroll
;                 for (int bj = 0; bj < 2; ++bj) {
;                     const int c = col0 + bj * 128;
;                     f32x4 v0 = acc[ai][bj][m][0], v1 = acc[ai][bj][m][1];
;                     if (MODE == 1) {
;                         const float* rp = res + (size_t)row * ldres + c;
;                         v0 += *(const f32x4*)rp; v1 += *(const f32x4*)(rp + 4);
;                     }
;                     if (MODE == 3) {
;                         const h16x8 r8 = *(const h16x8*)(res16 + (size_t)row * ldres + c);
; #pragma unroll
;                         for (int j = 0; j < 4; ++j) { v0[j] += (float)r8[j]; v1[j] += (float)r8[4 + j]; }
;                     }
;                     if (MODE == 1 || MODE == 3) {
;                         ss += v0[0] * v0[0] + v0[1] * v0[1] + v0[2] * v0[2] + v0[3] * v0[3] + v1[0] * v1[0] + v1[1] * v1[1] + v1[2] * v1[2] + v1[3] * v1[3];
;                     }
;                     if (MODE == 2) {
; #pragma unroll
;                         for (int j = 0; j < 4; ++j) { float a = fmaxf(v0[j] * rstd, 0.f), b = fmaxf(v1[j] * rstd, 0.f); v0[j] = a * a; v1[j] = b * b; }
;                     }
;                     *(h16x8*)(o16 + (size_t)row * ld16 + c) = pack8(v0, v1);
	v_pk_mul_f32 v[48:49], v[48:49], v[48:49]
	v_pk_mul_f32 v[50:51], v[50:51], v[50:51]
	v_cvt_pk_f16_f32 v52, v52, v53
	v_cvt_pk_f16_f32 v53, v54, v55
	v_cvt_pk_f16_f32 v54, v48, v49
	v_cvt_pk_f16_f32 v55, v50, v51
	s_nop 1
	v_mov_b32_dpp v192, v52 row_ror:8 row_mask:0xf bank_mask:0xf
	v_mov_b32_dpp v193, v53 row_ror:8 row_mask:0xf bank_mask:0xf
	v_mov_b32_dpp v194, v54 row_ror:8 row_mask:0xf bank_mask:0xf
	v_mov_b32_dpp v195, v55 row_ror:8 row_mask:0xf bank_mask:0xf
	v_cndmask_b32_e64 v52, v192, v60, s[98:99]
	v_cndmask_b32_e64 v53, v193, v61, s[98:99]
	v_cndmask_b32_e64 v54, v194, v62, s[98:99]
	v_cndmask_b32_e64 v55, v195, v63, s[98:99]
	v_cndmask_b32_e64 v192, v60, v192, s[98:99]
	v_cndmask_b32_e64 v193, v61, v193, s[98:99]
	v_cndmask_b32_e64 v194, v62, v194, s[98:99]
	v_cndmask_b32_e64 v195, v63, v195, s[98:99]
	v_lshl_add_u64 v[196:197], v[164:165], 0, v[214:215]
	v_lshl_add_u64 v[198:199], v[164:165], 0, v[216:217]
	global_store_dwordx4 v[196:197], v[52:55], off sc0 sc1 nt
	global_store_dwordx4 v[198:199], v[192:195], off sc0 sc1 nt
	s_mov_b32 s100, 0x20000
	s_mov_b32 s101, 0
	v_lshl_add_u64 v[164:165], v[164:165], 0, s[100:101]
	v_fmamk_f32 v190, v186, 0x3a800000, v213
	v_mul_f32_e32 v191, 0x4b800000, v190
	v_cmp_gt_f32_e64 s[100:101], s53, v190
	s_nop 1
	v_cndmask_b32_e64 v190, v190, v191, s[100:101]
	v_rsq_f32_e32 v190, v190
	s_nop 0
	v_mul_f32_e32 v191, 0x45800000, v190
	v_cndmask_b32_e64 v190, v190, v191, s[100:101]
	v_pk_mul_f32 v[44:45], v[44:45], v[190:191] op_sel_hi:[1,0]
	v_pk_mul_f32 v[46:47], v[46:47], v[190:191] op_sel_hi:[1,0]
	v_pk_mul_f32 v[40:41], v[40:41], v[190:191] op_sel_hi:[1,0]
	v_pk_mul_f32 v[42:43], v[42:43], v[190:191] op_sel_hi:[1,0]
	v_max_f32_e32 v44, 0, v44
	v_max_f32_e32 v45, 0, v45
	v_max_f32_e32 v46, 0, v46
	v_max_f32_e32 v47, 0, v47
	v_max_f32_e32 v40, 0, v40
	v_max_f32_e32 v41, 0, v41
	v_max_f32_e32 v42, 0, v42
	v_max_f32_e32 v43, 0, v43
	v_pk_mul_f32 v[44:45], v[44:45], v[44:45]
	v_pk_mul_f32 v[46:47], v[46:47], v[46:47]
	v_pk_mul_f32 v[40:41], v[40:41], v[40:41]
	v_pk_mul_f32 v[42:43], v[42:43], v[42:43]
	v_cvt_pk_f16_f32 v44, v44, v45
	v_cvt_pk_f16_f32 v45, v46, v47
	v_cvt_pk_f16_f32 v46, v40, v41
	v_cvt_pk_f16_f32 v47, v42, v43
	v_pk_mul_f32 v[36:37], v[36:37], v[190:191] op_sel_hi:[1,0]
	v_pk_mul_f32 v[38:39], v[38:39], v[190:191] op_sel_hi:[1,0]
	v_pk_mul_f32 v[32:33], v[32:33], v[190:191] op_sel_hi:[1,0]
	v_pk_mul_f32 v[34:35], v[34:35], v[190:191] op_sel_hi:[1,0]
	v_max_f32_e32 v36, 0, v36
	v_max_f32_e32 v37, 0, v37
	v_max_f32_e32 v38, 0, v38
	v_max_f32_e32 v39, 0, v39
	v_max_f32_e32 v32, 0, v32
	v_max_f32_e32 v33, 0, v33
	v_max_f32_e32 v34, 0, v34
	v_max_f32_e32 v35, 0, v35
	v_pk_mul_f32 v[36:37], v[36:37], v[36:37]
	v_pk_mul_f32 v[38:39], v[38:39], v[38:39]
	v_pk_mul_f32 v[32:33], v[32:33], v[32:33]
	v_pk_mul_f32 v[34:35], v[34:35], v[34:35]
	v_cvt_pk_f16_f32 v36, v36, v37
	v_cvt_pk_f16_f32 v37, v38, v39
	v_cvt_pk_f16_f32 v38, v32, v33
	v_cvt_pk_f16_f32 v39, v34, v35
	s_nop 1
	v_mov_b32_dpp v204, v36 row_ror:8 row_mask:0xf bank_mask:0xf
	v_mov_b32_dpp v205, v37 row_ror:8 row_mask:0xf bank_mask:0xf
	v_mov_b32_dpp v206, v38 row_ror:8 row_mask:0xf bank_mask:0xf
	v_mov_b32_dpp v207, v39 row_ror:8 row_mask:0xf bank_mask:0xf
	v_cndmask_b32_e64 v36, v204, v44, s[98:99]
	v_cndmask_b32_e64 v37, v205, v45, s[98:99]
	v_cndmask_b32_e64 v38, v206, v46, s[98:99]
	v_cndmask_b32_e64 v39, v207, v47, s[98:99]
	v_cndmask_b32_e64 v204, v44, v204, s[98:99]
	v_cndmask_b32_e64 v205, v45, v205, s[98:99]
	v_cndmask_b32_e64 v206, v46, v206, s[98:99]
	v_cndmask_b32_e64 v207, v47, v207, s[98:99]
	v_lshl_add_u64 v[208:209], v[164:165], 0, v[214:215]
	v_lshl_add_u64 v[210:211], v[164:165], 0, v[216:217]
	global_store_dwordx4 v[208:209], v[36:39], off sc0 sc1 nt
	global_store_dwordx4 v[210:211], v[204:207], off sc0 sc1 nt
	s_mov_b32 s100, 0x20000
	s_mov_b32 s101, 0
	v_lshl_add_u64 v[164:165], v[164:165], 0, s[100:101]
	v_fmamk_f32 v190, v187, 0x3a800000, v213
	v_mul_f32_e32 v191, 0x4b800000, v190
	v_cmp_gt_f32_e64 s[100:101], s53, v190
	s_nop 1
	v_cndmask_b32_e64 v190, v190, v191, s[100:101]
	v_rsq_f32_e32 v190, v190
	s_nop 0
	v_mul_f32_e32 v191, 0x45800000, v190
	v_cndmask_b32_e64 v190, v190, v191, s[100:101]
	v_pk_mul_f32 v[28:29], v[28:29], v[190:191] op_sel_hi:[1,0]
	v_pk_mul_f32 v[30:31], v[30:31], v[190:191] op_sel_hi:[1,0]
	v_pk_mul_f32 v[24:25], v[24:25], v[190:191] op_sel_hi:[1,0]
	v_pk_mul_f32 v[26:27], v[26:27], v[190:191] op_sel_hi:[1,0]
	v_max_f32_e32 v28, 0, v28
	v_max_f32_e32 v29, 0, v29
	v_max_f32_e32 v30, 0, v30
	v_max_f32_e32 v31, 0, v31
	v_max_f32_e32 v24, 0, v24
	v_max_f32_e32 v25, 0, v25
	v_max_f32_e32 v26, 0, v26
	v_max_f32_e32 v27, 0, v27
; #define PG8_WAIT_V(n) asm volatile("s_waitcnt vmcnt(" #n ")" ::: "memory")
; #define PG8_BAR __builtin_amdgcn_s_barrier()
; template <class Epi>
; __device__ __forceinline__ void gemm_phase(LAS unsigned char* lds, const Gemm g, const StaticOrder& S, const Epi& E) {
;     ...
;     PG8_WAIT_V(0);
;     if (wr == 0) PG8_BAR;
;     __device__ __forceinline__ void operator()(const f32x4 (&acc)[2][2][4][2], const pg8::Unit& u, int wr, int wc, int fr, int fq) const {
;     ...
;                 const int row = row0 + ai * 128 + m * 16;
;                 float ss = 0.f, rstd = 1.f;
;                 if (MODE == 2) rstd = rsqrtf(rowss[row] * (1.f / 1024.f) + EPS);
; #pragma unroll
;                 for (int bj = 0; bj < 2; ++bj) {
;                     const int c = col0 + bj * 128;
;                     f32x4 v0 = acc[ai][bj][m][0], v1 = acc[ai][bj][m][1];
;                     if (MODE == 1) {
;                         const float* rp = res + (size_t)row * ldres + c;
;                         v0 += *(const f32x4*)rp; v1 += *(const f32x4*)(rp + 4);
;                     }
;                     if (MODE == 3) {
;                         const h16x8 r8 = *(const h16x8*)(res16 + (size_t)row * ldres + c);
; #pragma unroll
;                         for (int j = 0; j < 4; ++j) { v0[j] += (float)r8[j]; v1[j] += (float)r8[4 + j]; }
;                     }
;                     if (MODE == 1 || MODE == 3) {
;                         ss += v0[0] * v0[0] + v0[1] * v0[1] + v0[2] * v0[2] + v0[3] * v0[3] + v1[0] * v1[0] + v1[1] * v1[1] + v1[2] * v1[2] + v1[3] * v1[3];
;                     }
;                     if (MODE == 2) {
; #pragma unroll
;                         for (int j = 0; j < 4; ++j) { float a = fmaxf(v0[j] * rstd, 0.f), b = fmaxf(v1[j] * rstd, 0.f); v0[j] = a * a; v1[j] = b * b; }
;                     }
;                     *(h16x8*)(o16 + (size_t)row * ld16 + c) = pack8(v0, v1);
	v_pk_mul_f32 v[28:29], v[28:29], v[28:29]
	v_pk_mul_f32 v[30:31], v[30:31], v[30:31]
	v_pk_mul_f32 v[24:25], v[24:25], v[24:25]
	v_pk_mul_f32 v[26:27], v[26:27], v[26:27]
	v_cvt_pk_f16_f32 v28, v28, v29
	v_cvt_pk_f16_f32 v29, v30, v31
	v_cvt_pk_f16_f32 v30, v24, v25
	v_cvt_pk_f16_f32 v31, v26, v27
	v_pk_mul_f32 v[20:21], v[20:21], v[190:191] op_sel_hi:[1,0]
	v_pk_mul_f32 v[22:23], v[22:23], v[190:191] op_sel_hi:[1,0]
	v_pk_mul_f32 v[16:17], v[16:17], v[190:191] op_sel_hi:[1,0]
	v_pk_mul_f32 v[18:19], v[18:19], v[190:191] op_sel_hi:[1,0]
	v_max_f32_e32 v20, 0, v20
	v_max_f32_e32 v21, 0, v21
	v_max_f32_e32 v22, 0, v22
	v_max_f32_e32 v23, 0, v23
	v_max_f32_e32 v16, 0, v16
	v_max_f32_e32 v17, 0, v17
	v_max_f32_e32 v18, 0, v18
	v_max_f32_e32 v19, 0, v19
	v_pk_mul_f32 v[20:21], v[20:21], v[20:21]
	v_pk_mul_f32 v[22:23], v[22:23], v[22:23]
	v_pk_mul_f32 v[16:17], v[16:17], v[16:17]
	v_pk_mul_f32 v[18:19], v[18:19], v[18:19]
	v_cvt_pk_f16_f32 v20, v20, v21
	v_cvt_pk_f16_f32 v21, v22, v23
	v_cvt_pk_f16_f32 v22, v16, v17
	v_cvt_pk_f16_f32 v23, v18, v19
	s_nop 1
	v_mov_b32_dpp v192, v20 row_ror:8 row_mask:0xf bank_mask:0xf
	v_mov_b32_dpp v193, v21 row_ror:8 row_mask:0xf bank_mask:0xf
	v_mov_b32_dpp v194, v22 row_ror:8 row_mask:0xf bank_mask:0xf
	v_mov_b32_dpp v195, v23 row_ror:8 row_mask:0xf bank_mask:0xf
	v_cndmask_b32_e64 v20, v192, v28, s[98:99]
	v_cndmask_b32_e64 v21, v193, v29, s[98:99]
	v_cndmask_b32_e64 v22, v194, v30, s[98:99]
	v_cndmask_b32_e64 v23, v195, v31, s[98:99]
	v_cndmask_b32_e64 v192, v28, v192, s[98:99]
	v_cndmask_b32_e64 v193, v29, v193, s[98:99]
	v_cndmask_b32_e64 v194, v30, v194, s[98:99]
	v_cndmask_b32_e64 v195, v31, v195, s[98:99]
	v_lshl_add_u64 v[196:197], v[164:165], 0, v[214:215]
	v_lshl_add_u64 v[198:199], v[164:165], 0, v[216:217]
	global_store_dwordx4 v[196:197], v[20:23], off sc0 sc1 nt
	global_store_dwordx4 v[198:199], v[192:195], off sc0 sc1 nt
	s_mov_b32 s100, 0x20000
	s_mov_b32 s101, 0
	v_lshl_add_u64 v[164:165], v[164:165], 0, s[100:101]
	v_fmamk_f32 v190, v188, 0x3a800000, v213
	v_mul_f32_e32 v191, 0x4b800000, v190
	v_cmp_gt_f32_e64 s[100:101], s53, v190
	s_nop 1
	v_cndmask_b32_e64 v190, v190, v191, s[100:101]
	v_rsq_f32_e32 v190, v190
	s_nop 0
	v_mul_f32_e32 v191, 0x45800000, v190
	v_cndmask_b32_e64 v190, v190, v191, s[100:101]
	v_pk_mul_f32 v[12:13], v[12:13], v[190:191] op_sel_hi:[1,0]
	v_pk_mul_f32 v[14:15], v[14:15], v[190:191] op_sel_hi:[1,0]
	v_pk_mul_f32 v[8:9], v[8:9], v[190:191] op_sel_hi:[1,0]
	v_pk_mul_f32 v[10:11], v[10:11], v[190:191] op_sel_hi:[1,0]
	v_max_f32_e32 v12, 0, v12
	v_max_f32_e32 v13, 0, v13
	v_max_f32_e32 v14, 0, v14
	v_max_f32_e32 v15, 0, v15
	v_max_f32_e32 v8, 0, v8
	v_max_f32_e32 v9, 0, v9
	v_max_f32_e32 v10, 0, v10
	v_max_f32_e32 v11, 0, v11
	v_pk_mul_f32 v[12:13], v[12:13], v[12:13]
	v_pk_mul_f32 v[14:15], v[14:15], v[14:15]
	v_pk_mul_f32 v[8:9], v[8:9], v[8:9]
	v_pk_mul_f32 v[10:11], v[10:11], v[10:11]
	v_cvt_pk_f16_f32 v12, v12, v13
	v_cvt_pk_f16_f32 v13, v14, v15
	v_cvt_pk_f16_f32 v14, v8, v9
	v_cvt_pk_f16_f32 v15, v10, v11
	v_pk_mul_f32 v[4:5], v[4:5], v[190:191] op_sel_hi:[1,0]
	v_pk_mul_f32 v[6:7], v[6:7], v[190:191] op_sel_hi:[1,0]
	v_pk_mul_f32 v[0:1], v[0:1], v[190:191] op_sel_hi:[1,0]
	v_pk_mul_f32 v[2:3], v[2:3], v[190:191] op_sel_hi:[1,0]
	v_max_f32_e32 v4, 0, v4
	v_max_f32_e32 v5, 0, v5
	v_max_f32_e32 v6, 0, v6
	v_max_f32_e32 v7, 0, v7
	v_max_f32_e32 v0, 0, v0
	v_max_f32_e32 v1, 0, v1
	v_max_f32_e32 v2, 0, v2
	v_max_f32_e32 v3, 0, v3
	v_pk_mul_f32 v[4:5], v[4:5], v[4:5]
	v_pk_mul_f32 v[6:7], v[6:7], v[6:7]
	v_pk_mul_f32 v[0:1], v[0:1], v[0:1]
	v_pk_mul_f32 v[2:3], v[2:3], v[2:3]
	v_cvt_pk_f16_f32 v4, v4, v5
	v_cvt_pk_f16_f32 v5, v6, v7
	v_cvt_pk_f16_f32 v6, v0, v1
	v_cvt_pk_f16_f32 v7, v2, v3
	s_nop 1
	v_mov_b32_dpp v204, v4 row_ror:8 row_mask:0xf bank_mask:0xf
	v_mov_b32_dpp v205, v5 row_ror:8 row_mask:0xf bank_mask:0xf
	v_mov_b32_dpp v206, v6 row_ror:8 row_mask:0xf bank_mask:0xf
	v_mov_b32_dpp v207, v7 row_ror:8 row_mask:0xf bank_mask:0xf
	v_cndmask_b32_e64 v4, v204, v12, s[98:99]
	v_cndmask_b32_e64 v5, v205, v13, s[98:99]
	v_cndmask_b32_e64 v6, v206, v14, s[98:99]
	v_cndmask_b32_e64 v7, v207, v15, s[98:99]
	v_cndmask_b32_e64 v204, v12, v204, s[98:99]
	v_cndmask_b32_e64 v205, v13, v205, s[98:99]
	v_cndmask_b32_e64 v206, v14, v206, s[98:99]
	v_cndmask_b32_e64 v207, v15, v207, s[98:99]
	v_lshl_add_u64 v[208:209], v[164:165], 0, v[214:215]
	v_lshl_add_u64 v[210:211], v[164:165], 0, v[216:217]
	global_store_dwordx4 v[208:209], v[4:7], off sc0 sc1 nt
	global_store_dwordx4 v[210:211], v[204:207], off sc0 sc1 nt
	s_and_b64 vcc, exec, s[6:7]
	s_cbranch_vccz .LBB0_476
	s_waitcnt vmcnt(0)
	s_cmpk_gt_u32 s41, 0xff
	s_cbranch_scc1 .LBB0_487
	s_barrier

;     __device__ __forceinline__ void operator()(f32x4 (&acc)[2][2][4][2], const pg8::Unit& u, int wr, int wc, int fr, int fq) const {
;     ...
; #pragma unroll
;         for (int ai = 0; ai < 2; ++ai)
; #pragma unroll
;             for (int m = 0; m < 4; ++m) {
;                 const int row = row0 + ai * 128 + m * 16;
;                 const float rstd = rsqrtf(__hip_atomic_load(rowss + row, __ATOMIC_RELAXED, __HIP_MEMORY_SCOPE_AGENT) * (1.f / 1024.f) + EPS);
; #pragma unroll
;                 for (int bj = 0; bj < 2; ++bj) {
;                     const int c = col0 + bj * 128;
;                     const f32x4 w0 = *(const f32x4*)(nw + c), w1 = *(const f32x4*)(nw + c + 4);
;                     float* op = out + (size_t)row * D + c;
;                     *(f32x4*)op = acc[ai][bj][m][0] * rstd * w0; *(f32x4*)(op + 4) = acc[ai][bj][m][1] * rstd * w1;
;                 }
;             }
.LBB0_605:
	s_or_b64 exec, exec, s[4:5]
	s_barrier
	v_mov_b32_e32 v250, 0x1b71a40
	global_load_dword v251, v250, s[82:83] sc1
	v_cmp_gt_u32_e64 s[98:99], 8, v131
	v_mov_b32_e32 v240, 0xffff8010
	v_cndmask_b32_e64 v236, v240, 0, s[98:99]
	v_cndmask_b32_e64 v237, -1, 0, s[98:99]
	v_mov_b32_e32 v240, 0x8010
	v_cndmask_b32_e64 v238, 0, v240, s[98:99]
	v_mov_b32_e32 v239, 0
	global_load_dword v147, v[112:113], off sc1
	v_lshlrev_b64 v[166:167], 2, v[140:141]
	v_lshl_add_u64 v[140:141], s[60:61], 0, v[166:167]
	global_load_dwordx4 v[168:171], v[140:141], off
	global_load_dwordx4 v[172:175], v[140:141], off offset:16
	v_mov_b32_e32 v137, 0x358637bd
	s_mov_b32 s0, 0x800000
	v_lshlrev_b64 v[138:139], 12, v[138:139]
	v_lshl_add_u64 v[138:139], s[62:63], 0, v[138:139]
	v_lshl_add_u64 v[138:139], v[138:139], 0, v[166:167]
	v_lshlrev_b64 v[104:105], 12, v[104:105]
	v_lshl_add_u64 v[104:105], s[62:63], 0, v[104:105]
	v_lshl_add_u64 v[104:105], v[104:105], 0, v[166:167]
	v_lshlrev_b64 v[88:89], 12, v[88:89]
	v_lshl_add_u64 v[88:89], s[62:63], 0, v[88:89]
	v_lshl_add_u64 v[88:89], v[88:89], 0, v[166:167]
	v_lshlrev_b64 v[72:73], 12, v[72:73]
	v_lshl_add_u64 v[72:73], s[62:63], 0, v[72:73]
	v_lshl_add_u64 v[72:73], v[72:73], 0, v[166:167]
	v_lshlrev_b64 v[56:57], 12, v[56:57]
	v_lshl_add_u64 v[56:57], s[62:63], 0, v[56:57]
	v_lshl_add_u64 v[56:57], v[56:57], 0, v[166:167]
	v_lshlrev_b64 v[40:41], 12, v[40:41]
	v_lshl_add_u64 v[40:41], s[62:63], 0, v[40:41]
	v_lshl_add_u64 v[40:41], v[40:41], 0, v[166:167]
	v_lshlrev_b64 v[24:25], 12, v[24:25]
	v_lshl_add_u64 v[24:25], s[62:63], 0, v[24:25]
	v_lshl_add_u64 v[24:25], v[24:25], 0, v[166:167]
	s_waitcnt vmcnt(2)
	v_fmamk_f32 v147, v147, 0x3a800000, v137
	v_mul_f32_e32 v176, 0x4b800000, v147
	v_cmp_gt_f32_e32 vcc, s0, v147
	s_nop 1
	v_cndmask_b32_e32 v147, v147, v176, vcc
	v_rsq_f32_e32 v147, v147
	s_nop 0
	v_mul_f32_e32 v176, 0x45800000, v147
	v_cndmask_b32_e32 v176, v147, v176, vcc
	v_pk_mul_f32 v[142:143], v[142:143], v[176:177] op_sel_hi:[1,0]
	v_pk_mul_f32 v[126:127], v[126:127], v[176:177] op_sel_hi:[1,0]
	v_pk_mul_f32 v[178:179], v[124:125], v[176:177] op_sel_hi:[1,0]
	v_pk_mul_f32 v[180:181], v[122:123], v[176:177] op_sel_hi:[1,0]
	s_waitcnt vmcnt(1)
	v_pk_mul_f32 v[124:125], v[170:171], v[126:127]
	v_pk_mul_f32 v[122:123], v[168:169], v[142:143]
	s_waitcnt vmcnt(0)
	v_pk_mul_f32 v[170:171], v[174:175], v[180:181]
	v_pk_mul_f32 v[168:169], v[172:173], v[178:179]
	s_nop 1
	v_mov_b32_dpp v228, v168 row_ror:8 row_mask:0xf bank_mask:0xf
	v_mov_b32_dpp v229, v169 row_ror:8 row_mask:0xf bank_mask:0xf
	v_mov_b32_dpp v230, v170 row_ror:8 row_mask:0xf bank_mask:0xf
	v_mov_b32_dpp v231, v171 row_ror:8 row_mask:0xf bank_mask:0xf
	v_cndmask_b32_e64 v168, v228, v122, s[98:99]
	v_cndmask_b32_e64 v169, v229, v123, s[98:99]
	v_cndmask_b32_e64 v170, v230, v124, s[98:99]
	v_cndmask_b32_e64 v171, v231, v125, s[98:99]
	v_cndmask_b32_e64 v228, v122, v228, s[98:99]
	v_cndmask_b32_e64 v229, v123, v229, s[98:99]
	v_cndmask_b32_e64 v230, v124, v230, s[98:99]
	v_cndmask_b32_e64 v231, v125, v231, s[98:99]
	v_lshl_add_u64 v[232:233], v[138:139], 0, v[236:237]
	v_lshl_add_u64 v[234:235], v[138:139], 0, v[238:239]
	global_store_dwordx4 v[232:233], v[168:171], off sc0 sc1 nt
	global_store_dwordx4 v[234:235], v[228:231], off sc0 sc1 nt
	global_load_dwordx4 v[122:125], v[140:141], off offset:512
	s_nop 0
	global_load_dwordx4 v[168:171], v[140:141], off offset:528
	v_pk_mul_f32 v[118:119], v[118:119], v[176:177] op_sel_hi:[1,0]
	v_pk_mul_f32 v[120:121], v[120:121], v[176:177] op_sel_hi:[1,0]
	v_pk_mul_f32 v[126:127], v[114:115], v[176:177] op_sel_hi:[1,0]
	v_pk_mul_f32 v[142:143], v[116:117], v[176:177] op_sel_hi:[1,0]
	s_waitcnt vmcnt(1)
	v_pk_mul_f32 v[114:115], v[122:123], v[120:121]
	v_pk_mul_f32 v[116:117], v[124:125], v[118:119]
	s_waitcnt vmcnt(0)
	v_pk_mul_f32 v[118:119], v[168:169], v[142:143]
	v_pk_mul_f32 v[120:121], v[170:171], v[126:127]
	s_nop 1
	v_mov_b32_dpp v228, v118 row_ror:8 row_mask:0xf bank_mask:0xf
	v_mov_b32_dpp v229, v119 row_ror:8 row_mask:0xf bank_mask:0xf
	v_mov_b32_dpp v230, v120 row_ror:8 row_mask:0xf bank_mask:0xf
	v_mov_b32_dpp v231, v121 row_ror:8 row_mask:0xf bank_mask:0xf
	v_cndmask_b32_e64 v118, v228, v114, s[98:99]
	v_cndmask_b32_e64 v119, v229, v115, s[98:99]
	v_cndmask_b32_e64 v120, v230, v116, s[98:99]
	v_cndmask_b32_e64 v121, v231, v117, s[98:99]
	v_cndmask_b32_e64 v228, v114, v228, s[98:99]
	v_cndmask_b32_e64 v229, v115, v229, s[98:99]
	v_cndmask_b32_e64 v230, v116, v230, s[98:99]
	v_cndmask_b32_e64 v231, v117, v231, s[98:99]
	v_lshl_add_u64 v[232:233], v[138:139], 0, v[236:237]
	v_lshl_add_u64 v[234:235], v[138:139], 0, v[238:239]
	global_store_dwordx4 v[232:233], v[118:121], off offset:512 sc0 sc1 nt
	global_store_dwordx4 v[234:235], v[228:231], off offset:512 sc0 sc1 nt
	global_load_dword v122, v[152:153], off sc1
	s_nop 0
	global_load_dwordx4 v[114:117], v[140:141], off
	global_load_dwordx4 v[118:121], v[140:141], off offset:16
	s_waitcnt vmcnt(2)
	v_fmamk_f32 v122, v122, 0x3a800000, v137
	v_mul_f32_e32 v123, 0x4b800000, v122
	v_cmp_gt_f32_e32 vcc, s0, v122
	s_nop 1
	v_cndmask_b32_e32 v122, v122, v123, vcc
	v_rsq_f32_e32 v124, v122
	v_lshlrev_b64 v[122:123], 12, v[144:145]
	v_lshl_add_u64 v[122:123], s[62:63], 0, v[122:123]
	v_lshl_add_u64 v[122:123], v[122:123], 0, v[166:167]
	v_mul_f32_e32 v125, 0x45800000, v124
	v_cndmask_b32_e32 v124, v124, v125, vcc
	v_pk_mul_f32 v[126:127], v[148:149], v[124:125] op_sel_hi:[1,0]
	v_pk_mul_f32 v[110:111], v[110:111], v[124:125] op_sel_hi:[1,0]
	v_pk_mul_f32 v[138:139], v[108:109], v[124:125] op_sel_hi:[1,0]
	v_pk_mul_f32 v[142:143], v[106:107], v[124:125] op_sel_hi:[1,0]
	s_waitcnt vmcnt(1)
;     __device__ __forceinline__ void operator()(f32x4 (&acc)[2][2][4][2], const pg8::Unit& u, int wr, int wc, int fr, int fq) const {
;     ...
; #pragma unroll
;         for (int ai = 0; ai < 2; ++ai)
; #pragma unroll
;             for (int m = 0; m < 4; ++m) {
;                 const int row = row0 + ai * 128 + m * 16;
;                 const float rstd = rsqrtf(__hip_atomic_load(rowss + row, __ATOMIC_RELAXED, __HIP_MEMORY_SCOPE_AGENT) * (1.f / 1024.f) + EPS);
; #pragma unroll
;                 for (int bj = 0; bj < 2; ++bj) {
;                     const int c = col0 + bj * 128;
;                     const f32x4 w0 = *(const f32x4*)(nw + c), w1 = *(const f32x4*)(nw + c + 4);
;                     float* op = out + (size_t)row * D + c;
;                     *(f32x4*)op = acc[ai][bj][m][0] * rstd * w0; *(f32x4*)(op + 4) = acc[ai][bj][m][1] * rstd * w1;
;                 }
;             }
	v_pk_mul_f32 v[108:109], v[116:117], v[110:111]
	v_pk_mul_f32 v[106:107], v[114:115], v[126:127]
	s_waitcnt vmcnt(0)
	v_pk_mul_f32 v[116:117], v[120:121], v[142:143]
	v_pk_mul_f32 v[114:115], v[118:119], v[138:139]
	s_nop 1
	v_mov_b32_dpp v228, v114 row_ror:8 row_mask:0xf bank_mask:0xf
	v_mov_b32_dpp v229, v115 row_ror:8 row_mask:0xf bank_mask:0xf
	v_mov_b32_dpp v230, v116 row_ror:8 row_mask:0xf bank_mask:0xf
	v_mov_b32_dpp v231, v117 row_ror:8 row_mask:0xf bank_mask:0xf
	v_cndmask_b32_e64 v114, v228, v106, s[98:99]
	v_cndmask_b32_e64 v115, v229, v107, s[98:99]
	v_cndmask_b32_e64 v116, v230, v108, s[98:99]
	v_cndmask_b32_e64 v117, v231, v109, s[98:99]
	v_cndmask_b32_e64 v228, v106, v228, s[98:99]
	v_cndmask_b32_e64 v229, v107, v229, s[98:99]
	v_cndmask_b32_e64 v230, v108, v230, s[98:99]
	v_cndmask_b32_e64 v231, v109, v231, s[98:99]
	v_lshl_add_u64 v[232:233], v[122:123], 0, v[236:237]
	v_lshl_add_u64 v[234:235], v[122:123], 0, v[238:239]
	global_store_dwordx4 v[232:233], v[114:117], off sc0 sc1 nt
	global_store_dwordx4 v[234:235], v[228:231], off sc0 sc1 nt
	global_load_dwordx4 v[106:109], v[140:141], off offset:512
	s_nop 0
	global_load_dwordx4 v[114:117], v[140:141], off offset:528
	v_pk_mul_f32 v[102:103], v[102:103], v[124:125] op_sel_hi:[1,0]
	v_pk_mul_f32 v[100:101], v[100:101], v[124:125] op_sel_hi:[1,0]
	v_pk_mul_f32 v[110:111], v[98:99], v[124:125] op_sel_hi:[1,0]
	v_pk_mul_f32 v[118:119], v[96:97], v[124:125] op_sel_hi:[1,0]
	s_waitcnt vmcnt(1)
	v_pk_mul_f32 v[96:97], v[106:107], v[100:101]
	v_pk_mul_f32 v[98:99], v[108:109], v[102:103]
	s_waitcnt vmcnt(0)
	v_pk_mul_f32 v[100:101], v[114:115], v[118:119]
	v_pk_mul_f32 v[102:103], v[116:117], v[110:111]
	s_nop 1
	v_mov_b32_dpp v228, v100 row_ror:8 row_mask:0xf bank_mask:0xf
	v_mov_b32_dpp v229, v101 row_ror:8 row_mask:0xf bank_mask:0xf
	v_mov_b32_dpp v230, v102 row_ror:8 row_mask:0xf bank_mask:0xf
	v_mov_b32_dpp v231, v103 row_ror:8 row_mask:0xf bank_mask:0xf
	v_cndmask_b32_e64 v100, v228, v96, s[98:99]
	v_cndmask_b32_e64 v101, v229, v97, s[98:99]
	v_cndmask_b32_e64 v102, v230, v98, s[98:99]
	v_cndmask_b32_e64 v103, v231, v99, s[98:99]
	v_cndmask_b32_e64 v228, v96, v228, s[98:99]
	v_cndmask_b32_e64 v229, v97, v229, s[98:99]
	v_cndmask_b32_e64 v230, v98, v230, s[98:99]
	v_cndmask_b32_e64 v231, v99, v231, s[98:99]
	v_lshl_add_u64 v[232:233], v[122:123], 0, v[236:237]
	v_lshl_add_u64 v[234:235], v[122:123], 0, v[238:239]
	global_store_dwordx4 v[232:233], v[100:103], off offset:512 sc0 sc1 nt
	global_store_dwordx4 v[234:235], v[228:231], off offset:512 sc0 sc1 nt
	global_load_dword v106, v[156:157], off sc1
	s_nop 0
	global_load_dwordx4 v[96:99], v[140:141], off
	global_load_dwordx4 v[100:103], v[140:141], off offset:16
	s_waitcnt vmcnt(2)
	v_fmamk_f32 v106, v106, 0x3a800000, v137
	v_mul_f32_e32 v107, 0x4b800000, v106
	v_cmp_gt_f32_e32 vcc, s0, v106
	s_nop 1
	v_cndmask_b32_e32 v106, v106, v107, vcc
	v_rsq_f32_e32 v106, v106
	s_nop 0
	v_mul_f32_e32 v107, 0x45800000, v106
	v_cndmask_b32_e32 v106, v106, v107, vcc
	v_pk_mul_f32 v[108:109], v[150:151], v[106:107] op_sel_hi:[1,0]
	v_pk_mul_f32 v[94:95], v[94:95], v[106:107] op_sel_hi:[1,0]
	v_pk_mul_f32 v[110:111], v[92:93], v[106:107] op_sel_hi:[1,0]
	v_pk_mul_f32 v[114:115], v[90:91], v[106:107] op_sel_hi:[1,0]
	s_waitcnt vmcnt(1)
	v_pk_mul_f32 v[92:93], v[98:99], v[94:95]
	v_pk_mul_f32 v[90:91], v[96:97], v[108:109]
	s_waitcnt vmcnt(0)
	v_pk_mul_f32 v[96:97], v[102:103], v[114:115]
	v_pk_mul_f32 v[94:95], v[100:101], v[110:111]
	s_nop 1
	v_mov_b32_dpp v228, v94 row_ror:8 row_mask:0xf bank_mask:0xf
	v_mov_b32_dpp v229, v95 row_ror:8 row_mask:0xf bank_mask:0xf
	v_mov_b32_dpp v230, v96 row_ror:8 row_mask:0xf bank_mask:0xf
	v_mov_b32_dpp v231, v97 row_ror:8 row_mask:0xf bank_mask:0xf
	v_cndmask_b32_e64 v94, v228, v90, s[98:99]
	v_cndmask_b32_e64 v95, v229, v91, s[98:99]
	v_cndmask_b32_e64 v96, v230, v92, s[98:99]
	v_cndmask_b32_e64 v97, v231, v93, s[98:99]
	v_cndmask_b32_e64 v228, v90, v228, s[98:99]
	v_cndmask_b32_e64 v229, v91, v229, s[98:99]
	v_cndmask_b32_e64 v230, v92, v230, s[98:99]
	v_cndmask_b32_e64 v231, v93, v231, s[98:99]
	v_lshl_add_u64 v[232:233], v[104:105], 0, v[236:237]
	v_lshl_add_u64 v[234:235], v[104:105], 0, v[238:239]
	global_store_dwordx4 v[232:233], v[94:97], off sc0 sc1 nt
	global_store_dwordx4 v[234:235], v[228:231], off sc0 sc1 nt
	global_load_dwordx4 v[90:93], v[140:141], off offset:512
	s_nop 0
	global_load_dwordx4 v[94:97], v[140:141], off offset:528
	v_pk_mul_f32 v[86:87], v[86:87], v[106:107] op_sel_hi:[1,0]
	v_pk_mul_f32 v[84:85], v[84:85], v[106:107] op_sel_hi:[1,0]
	v_pk_mul_f32 v[98:99], v[82:83], v[106:107] op_sel_hi:[1,0]
	v_pk_mul_f32 v[100:101], v[80:81], v[106:107] op_sel_hi:[1,0]
	s_waitcnt vmcnt(1)
	v_pk_mul_f32 v[80:81], v[90:91], v[84:85]
	v_pk_mul_f32 v[82:83], v[92:93], v[86:87]
	s_waitcnt vmcnt(0)
	v_pk_mul_f32 v[84:85], v[94:95], v[100:101]
	v_pk_mul_f32 v[86:87], v[96:97], v[98:99]
	s_nop 1
	v_mov_b32_dpp v228, v84 row_ror:8 row_mask:0xf bank_mask:0xf
	v_mov_b32_dpp v229, v85 row_ror:8 row_mask:0xf bank_mask:0xf
	v_mov_b32_dpp v230, v86 row_ror:8 row_mask:0xf bank_mask:0xf
	v_mov_b32_dpp v231, v87 row_ror:8 row_mask:0xf bank_mask:0xf
	v_cndmask_b32_e64 v84, v228, v80, s[98:99]
	v_cndmask_b32_e64 v85, v229, v81, s[98:99]
	v_cndmask_b32_e64 v86, v230, v82, s[98:99]
	v_cndmask_b32_e64 v87, v231, v83, s[98:99]
	v_cndmask_b32_e64 v228, v80, v228, s[98:99]
	v_cndmask_b32_e64 v229, v81, v229, s[98:99]
	v_cndmask_b32_e64 v230, v82, v230, s[98:99]
	v_cndmask_b32_e64 v231, v83, v231, s[98:99]
	v_lshl_add_u64 v[232:233], v[104:105], 0, v[236:237]
	v_lshl_add_u64 v[234:235], v[104:105], 0, v[238:239]
	global_store_dwordx4 v[232:233], v[84:87], off offset:512 sc0 sc1 nt
	global_store_dwordx4 v[234:235], v[228:231], off offset:512 sc0 sc1 nt
	global_load_dword v90, v[160:161], off sc1
	s_nop 0
	global_load_dwordx4 v[80:83], v[140:141], off
	global_load_dwordx4 v[84:87], v[140:141], off offset:16
	s_waitcnt vmcnt(2)
;     __device__ __forceinline__ void operator()(f32x4 (&acc)[2][2][4][2], const pg8::Unit& u, int wr, int wc, int fr, int fq) const {
;     ...
; #pragma unroll
;         for (int ai = 0; ai < 2; ++ai)
; #pragma unroll
;             for (int m = 0; m < 4; ++m) {
;                 const int row = row0 + ai * 128 + m * 16;
;                 const float rstd = rsqrtf(__hip_atomic_load(rowss + row, __ATOMIC_RELAXED, __HIP_MEMORY_SCOPE_AGENT) * (1.f / 1024.f) + EPS);
; #pragma unroll
;                 for (int bj = 0; bj < 2; ++bj) {
;                     const int c = col0 + bj * 128;
;                     const f32x4 w0 = *(const f32x4*)(nw + c), w1 = *(const f32x4*)(nw + c + 4);
;                     float* op = out + (size_t)row * D + c;
;                     *(f32x4*)op = acc[ai][bj][m][0] * rstd * w0; *(f32x4*)(op + 4) = acc[ai][bj][m][1] * rstd * w1;
;                 }
;             }
	v_fmamk_f32 v90, v90, 0x3a800000, v137
	v_mul_f32_e32 v91, 0x4b800000, v90
	v_cmp_gt_f32_e32 vcc, s0, v90
	s_nop 1
	v_cndmask_b32_e32 v90, v90, v91, vcc
	v_rsq_f32_e32 v90, v90
	s_nop 0
	v_mul_f32_e32 v91, 0x45800000, v90
	v_cndmask_b32_e32 v90, v90, v91, vcc
	v_pk_mul_f32 v[92:93], v[154:155], v[90:91] op_sel_hi:[1,0]
	v_pk_mul_f32 v[78:79], v[78:79], v[90:91] op_sel_hi:[1,0]
	v_pk_mul_f32 v[94:95], v[76:77], v[90:91] op_sel_hi:[1,0]
	v_pk_mul_f32 v[96:97], v[74:75], v[90:91] op_sel_hi:[1,0]
	s_waitcnt vmcnt(1)
	v_pk_mul_f32 v[76:77], v[82:83], v[78:79]
	v_pk_mul_f32 v[74:75], v[80:81], v[92:93]
	s_waitcnt vmcnt(0)
	v_pk_mul_f32 v[80:81], v[86:87], v[96:97]
	v_pk_mul_f32 v[78:79], v[84:85], v[94:95]
	s_nop 1
	v_mov_b32_dpp v228, v78 row_ror:8 row_mask:0xf bank_mask:0xf
	v_mov_b32_dpp v229, v79 row_ror:8 row_mask:0xf bank_mask:0xf
	v_mov_b32_dpp v230, v80 row_ror:8 row_mask:0xf bank_mask:0xf
	v_mov_b32_dpp v231, v81 row_ror:8 row_mask:0xf bank_mask:0xf
	v_cndmask_b32_e64 v78, v228, v74, s[98:99]
	v_cndmask_b32_e64 v79, v229, v75, s[98:99]
	v_cndmask_b32_e64 v80, v230, v76, s[98:99]
	v_cndmask_b32_e64 v81, v231, v77, s[98:99]
	v_cndmask_b32_e64 v228, v74, v228, s[98:99]
	v_cndmask_b32_e64 v229, v75, v229, s[98:99]
	v_cndmask_b32_e64 v230, v76, v230, s[98:99]
	v_cndmask_b32_e64 v231, v77, v231, s[98:99]
	v_lshl_add_u64 v[232:233], v[88:89], 0, v[236:237]
	v_lshl_add_u64 v[234:235], v[88:89], 0, v[238:239]
	global_store_dwordx4 v[232:233], v[78:81], off sc0 sc1 nt
	global_store_dwordx4 v[234:235], v[228:231], off sc0 sc1 nt
	global_load_dwordx4 v[74:77], v[140:141], off offset:512
	s_nop 0
	global_load_dwordx4 v[78:81], v[140:141], off offset:528
	v_pk_mul_f32 v[70:71], v[70:71], v[90:91] op_sel_hi:[1,0]
	v_pk_mul_f32 v[68:69], v[68:69], v[90:91] op_sel_hi:[1,0]
	v_pk_mul_f32 v[82:83], v[66:67], v[90:91] op_sel_hi:[1,0]
	v_pk_mul_f32 v[84:85], v[64:65], v[90:91] op_sel_hi:[1,0]
	s_waitcnt vmcnt(1)
	v_pk_mul_f32 v[64:65], v[74:75], v[68:69]
	v_pk_mul_f32 v[66:67], v[76:77], v[70:71]
	s_waitcnt vmcnt(0)
	v_pk_mul_f32 v[68:69], v[78:79], v[84:85]
	v_pk_mul_f32 v[70:71], v[80:81], v[82:83]
	s_nop 1
	v_mov_b32_dpp v228, v68 row_ror:8 row_mask:0xf bank_mask:0xf
	v_mov_b32_dpp v229, v69 row_ror:8 row_mask:0xf bank_mask:0xf
	v_mov_b32_dpp v230, v70 row_ror:8 row_mask:0xf bank_mask:0xf
	v_mov_b32_dpp v231, v71 row_ror:8 row_mask:0xf bank_mask:0xf
	v_cndmask_b32_e64 v68, v228, v64, s[98:99]
	v_cndmask_b32_e64 v69, v229, v65, s[98:99]
	v_cndmask_b32_e64 v70, v230, v66, s[98:99]
	v_cndmask_b32_e64 v71, v231, v67, s[98:99]
	v_cndmask_b32_e64 v228, v64, v228, s[98:99]
	v_cndmask_b32_e64 v229, v65, v229, s[98:99]
	v_cndmask_b32_e64 v230, v66, v230, s[98:99]
	v_cndmask_b32_e64 v231, v67, v231, s[98:99]
	v_lshl_add_u64 v[232:233], v[88:89], 0, v[236:237]
	v_lshl_add_u64 v[234:235], v[88:89], 0, v[238:239]
	global_store_dwordx4 v[232:233], v[68:71], off offset:512 sc0 sc1 nt
	global_store_dwordx4 v[234:235], v[228:231], off offset:512 sc0 sc1 nt
	global_load_dword v74, v[112:113], off offset:512 sc1
	s_nop 0
	global_load_dwordx4 v[64:67], v[140:141], off
	global_load_dwordx4 v[68:71], v[140:141], off offset:16
	s_waitcnt vmcnt(2)
	v_fmamk_f32 v74, v74, 0x3a800000, v137
	v_mul_f32_e32 v75, 0x4b800000, v74
	v_cmp_gt_f32_e32 vcc, s0, v74
	s_nop 1
	v_cndmask_b32_e32 v74, v74, v75, vcc
	v_rsq_f32_e32 v74, v74
	s_nop 0
	v_mul_f32_e32 v75, 0x45800000, v74
	v_cndmask_b32_e32 v74, v74, v75, vcc
	v_pk_mul_f32 v[76:77], v[158:159], v[74:75] op_sel_hi:[1,0]
	v_pk_mul_f32 v[62:63], v[62:63], v[74:75] op_sel_hi:[1,0]
	v_pk_mul_f32 v[78:79], v[60:61], v[74:75] op_sel_hi:[1,0]
	v_pk_mul_f32 v[80:81], v[58:59], v[74:75] op_sel_hi:[1,0]
	s_waitcnt vmcnt(1)
	v_pk_mul_f32 v[60:61], v[66:67], v[62:63]
	v_pk_mul_f32 v[58:59], v[64:65], v[76:77]
	s_waitcnt vmcnt(0)
	v_pk_mul_f32 v[64:65], v[70:71], v[80:81]
	v_pk_mul_f32 v[62:63], v[68:69], v[78:79]
	s_nop 1
	v_mov_b32_dpp v228, v62 row_ror:8 row_mask:0xf bank_mask:0xf
	v_mov_b32_dpp v229, v63 row_ror:8 row_mask:0xf bank_mask:0xf
	v_mov_b32_dpp v230, v64 row_ror:8 row_mask:0xf bank_mask:0xf
	v_mov_b32_dpp v231, v65 row_ror:8 row_mask:0xf bank_mask:0xf
	v_cndmask_b32_e64 v62, v228, v58, s[98:99]
	v_cndmask_b32_e64 v63, v229, v59, s[98:99]
	v_cndmask_b32_e64 v64, v230, v60, s[98:99]
	v_cndmask_b32_e64 v65, v231, v61, s[98:99]
	v_cndmask_b32_e64 v228, v58, v228, s[98:99]
	v_cndmask_b32_e64 v229, v59, v229, s[98:99]
	v_cndmask_b32_e64 v230, v60, v230, s[98:99]
	v_cndmask_b32_e64 v231, v61, v231, s[98:99]
	v_lshl_add_u64 v[232:233], v[72:73], 0, v[236:237]
	v_lshl_add_u64 v[234:235], v[72:73], 0, v[238:239]
	global_store_dwordx4 v[232:233], v[62:65], off sc0 sc1 nt
	global_store_dwordx4 v[234:235], v[228:231], off sc0 sc1 nt
	global_load_dwordx4 v[58:61], v[140:141], off offset:512
	s_nop 0
	global_load_dwordx4 v[62:65], v[140:141], off offset:528
	v_pk_mul_f32 v[54:55], v[54:55], v[74:75] op_sel_hi:[1,0]
	v_pk_mul_f32 v[52:53], v[52:53], v[74:75] op_sel_hi:[1,0]
	v_pk_mul_f32 v[66:67], v[50:51], v[74:75] op_sel_hi:[1,0]
	v_pk_mul_f32 v[68:69], v[48:49], v[74:75] op_sel_hi:[1,0]
	s_waitcnt vmcnt(1)
	v_pk_mul_f32 v[48:49], v[58:59], v[52:53]
	v_pk_mul_f32 v[50:51], v[60:61], v[54:55]
	s_waitcnt vmcnt(0)
;     __device__ __forceinline__ void operator()(f32x4 (&acc)[2][2][4][2], const pg8::Unit& u, int wr, int wc, int fr, int fq) const {
;     ...
; #pragma unroll
;         for (int ai = 0; ai < 2; ++ai)
; #pragma unroll
;             for (int m = 0; m < 4; ++m) {
;                 const int row = row0 + ai * 128 + m * 16;
;                 const float rstd = rsqrtf(__hip_atomic_load(rowss + row, __ATOMIC_RELAXED, __HIP_MEMORY_SCOPE_AGENT) * (1.f / 1024.f) + EPS);
; #pragma unroll
;                 for (int bj = 0; bj < 2; ++bj) {
;                     const int c = col0 + bj * 128;
;                     const f32x4 w0 = *(const f32x4*)(nw + c), w1 = *(const f32x4*)(nw + c + 4);
;                     float* op = out + (size_t)row * D + c;
;                     *(f32x4*)op = acc[ai][bj][m][0] * rstd * w0; *(f32x4*)(op + 4) = acc[ai][bj][m][1] * rstd * w1;
;                 }
;             }
	v_pk_mul_f32 v[52:53], v[62:63], v[68:69]
	v_pk_mul_f32 v[54:55], v[64:65], v[66:67]
	s_nop 1
	v_mov_b32_dpp v228, v52 row_ror:8 row_mask:0xf bank_mask:0xf
	v_mov_b32_dpp v229, v53 row_ror:8 row_mask:0xf bank_mask:0xf
	v_mov_b32_dpp v230, v54 row_ror:8 row_mask:0xf bank_mask:0xf
	v_mov_b32_dpp v231, v55 row_ror:8 row_mask:0xf bank_mask:0xf
	v_cndmask_b32_e64 v52, v228, v48, s[98:99]
	v_cndmask_b32_e64 v53, v229, v49, s[98:99]
	v_cndmask_b32_e64 v54, v230, v50, s[98:99]
	v_cndmask_b32_e64 v55, v231, v51, s[98:99]
	v_cndmask_b32_e64 v228, v48, v228, s[98:99]
	v_cndmask_b32_e64 v229, v49, v229, s[98:99]
	v_cndmask_b32_e64 v230, v50, v230, s[98:99]
	v_cndmask_b32_e64 v231, v51, v231, s[98:99]
	v_lshl_add_u64 v[232:233], v[72:73], 0, v[236:237]
	v_lshl_add_u64 v[234:235], v[72:73], 0, v[238:239]
	global_store_dwordx4 v[232:233], v[52:55], off offset:512 sc0 sc1 nt
	global_store_dwordx4 v[234:235], v[228:231], off offset:512 sc0 sc1 nt
	global_load_dword v58, v[112:113], off offset:576 sc1
	s_nop 0
	global_load_dwordx4 v[48:51], v[140:141], off
	global_load_dwordx4 v[52:55], v[140:141], off offset:16
	s_waitcnt vmcnt(2)
	v_fmamk_f32 v58, v58, 0x3a800000, v137
	v_mul_f32_e32 v59, 0x4b800000, v58
	v_cmp_gt_f32_e32 vcc, s0, v58
	s_nop 1
	v_cndmask_b32_e32 v58, v58, v59, vcc
	v_rsq_f32_e32 v58, v58
	s_nop 0
	v_mul_f32_e32 v59, 0x45800000, v58
	v_cndmask_b32_e32 v58, v58, v59, vcc
	v_pk_mul_f32 v[60:61], v[162:163], v[58:59] op_sel_hi:[1,0]
	v_pk_mul_f32 v[46:47], v[46:47], v[58:59] op_sel_hi:[1,0]
	v_pk_mul_f32 v[62:63], v[44:45], v[58:59] op_sel_hi:[1,0]
	v_pk_mul_f32 v[64:65], v[42:43], v[58:59] op_sel_hi:[1,0]
	s_waitcnt vmcnt(1)
	v_pk_mul_f32 v[44:45], v[50:51], v[46:47]
	v_pk_mul_f32 v[42:43], v[48:49], v[60:61]
	s_waitcnt vmcnt(0)
	v_pk_mul_f32 v[48:49], v[54:55], v[64:65]
	v_pk_mul_f32 v[46:47], v[52:53], v[62:63]
	s_nop 1
	v_mov_b32_dpp v228, v46 row_ror:8 row_mask:0xf bank_mask:0xf
	v_mov_b32_dpp v229, v47 row_ror:8 row_mask:0xf bank_mask:0xf
	v_mov_b32_dpp v230, v48 row_ror:8 row_mask:0xf bank_mask:0xf
	v_mov_b32_dpp v231, v49 row_ror:8 row_mask:0xf bank_mask:0xf
	v_cndmask_b32_e64 v46, v228, v42, s[98:99]
	v_cndmask_b32_e64 v47, v229, v43, s[98:99]
	v_cndmask_b32_e64 v48, v230, v44, s[98:99]
	v_cndmask_b32_e64 v49, v231, v45, s[98:99]
	v_cndmask_b32_e64 v228, v42, v228, s[98:99]
	v_cndmask_b32_e64 v229, v43, v229, s[98:99]
	v_cndmask_b32_e64 v230, v44, v230, s[98:99]
	v_cndmask_b32_e64 v231, v45, v231, s[98:99]
	v_lshl_add_u64 v[232:233], v[56:57], 0, v[236:237]
	v_lshl_add_u64 v[234:235], v[56:57], 0, v[238:239]
	global_store_dwordx4 v[232:233], v[46:49], off sc0 sc1 nt
	global_store_dwordx4 v[234:235], v[228:231], off sc0 sc1 nt
	global_load_dwordx4 v[42:45], v[140:141], off offset:512
	s_nop 0
	global_load_dwordx4 v[46:49], v[140:141], off offset:528
	v_pk_mul_f32 v[38:39], v[38:39], v[58:59] op_sel_hi:[1,0]
	v_pk_mul_f32 v[36:37], v[36:37], v[58:59] op_sel_hi:[1,0]
	v_pk_mul_f32 v[50:51], v[34:35], v[58:59] op_sel_hi:[1,0]
	v_pk_mul_f32 v[52:53], v[32:33], v[58:59] op_sel_hi:[1,0]
	s_waitcnt vmcnt(1)
	v_pk_mul_f32 v[32:33], v[42:43], v[36:37]
	v_pk_mul_f32 v[34:35], v[44:45], v[38:39]
	s_waitcnt vmcnt(0)
	v_pk_mul_f32 v[36:37], v[46:47], v[52:53]
	v_pk_mul_f32 v[38:39], v[48:49], v[50:51]
	s_nop 1
	v_mov_b32_dpp v228, v36 row_ror:8 row_mask:0xf bank_mask:0xf
	v_mov_b32_dpp v229, v37 row_ror:8 row_mask:0xf bank_mask:0xf
	v_mov_b32_dpp v230, v38 row_ror:8 row_mask:0xf bank_mask:0xf
	v_mov_b32_dpp v231, v39 row_ror:8 row_mask:0xf bank_mask:0xf
	v_cndmask_b32_e64 v36, v228, v32, s[98:99]
	v_cndmask_b32_e64 v37, v229, v33, s[98:99]
	v_cndmask_b32_e64 v38, v230, v34, s[98:99]
	v_cndmask_b32_e64 v39, v231, v35, s[98:99]
	v_cndmask_b32_e64 v228, v32, v228, s[98:99]
	v_cndmask_b32_e64 v229, v33, v229, s[98:99]
	v_cndmask_b32_e64 v230, v34, v230, s[98:99]
	v_cndmask_b32_e64 v231, v35, v231, s[98:99]
	v_lshl_add_u64 v[232:233], v[56:57], 0, v[236:237]
	v_lshl_add_u64 v[234:235], v[56:57], 0, v[238:239]
	global_store_dwordx4 v[232:233], v[36:39], off offset:512 sc0 sc1 nt
	global_store_dwordx4 v[234:235], v[228:231], off offset:512 sc0 sc1 nt
	global_load_dword v42, v[112:113], off offset:640 sc1
	s_nop 0
	global_load_dwordx4 v[32:35], v[140:141], off
	global_load_dwordx4 v[36:39], v[140:141], off offset:16
	s_waitcnt vmcnt(2)
	v_fmamk_f32 v42, v42, 0x3a800000, v137
	v_mul_f32_e32 v43, 0x4b800000, v42
	v_cmp_gt_f32_e32 vcc, s0, v42
	s_nop 1
	v_cndmask_b32_e32 v42, v42, v43, vcc
	v_rsq_f32_e32 v42, v42
	s_nop 0
	v_mul_f32_e32 v43, 0x45800000, v42
	v_cndmask_b32_e32 v42, v42, v43, vcc
	v_pk_mul_f32 v[44:45], v[164:165], v[42:43] op_sel_hi:[1,0]
	v_pk_mul_f32 v[30:31], v[30:31], v[42:43] op_sel_hi:[1,0]
	v_pk_mul_f32 v[46:47], v[28:29], v[42:43] op_sel_hi:[1,0]
	v_pk_mul_f32 v[48:49], v[26:27], v[42:43] op_sel_hi:[1,0]
	s_waitcnt vmcnt(1)
	v_pk_mul_f32 v[28:29], v[34:35], v[30:31]
	v_pk_mul_f32 v[26:27], v[32:33], v[44:45]
	s_waitcnt vmcnt(0)
;     __device__ __forceinline__ void operator()(f32x4 (&acc)[2][2][4][2], const pg8::Unit& u, int wr, int wc, int fr, int fq) const {
;     ...
; #pragma unroll
;         for (int ai = 0; ai < 2; ++ai)
; #pragma unroll
;             for (int m = 0; m < 4; ++m) {
;                 const int row = row0 + ai * 128 + m * 16;
;                 const float rstd = rsqrtf(__hip_atomic_load(rowss + row, __ATOMIC_RELAXED, __HIP_MEMORY_SCOPE_AGENT) * (1.f / 1024.f) + EPS);
; #pragma unroll
;                 for (int bj = 0; bj < 2; ++bj) {
;                     const int c = col0 + bj * 128;
;                     const f32x4 w0 = *(const f32x4*)(nw + c), w1 = *(const f32x4*)(nw + c + 4);
;                     float* op = out + (size_t)row * D + c;
;                     *(f32x4*)op = acc[ai][bj][m][0] * rstd * w0; *(f32x4*)(op + 4) = acc[ai][bj][m][1] * rstd * w1;
;                 }
;             }
	v_pk_mul_f32 v[32:33], v[38:39], v[48:49]
	v_pk_mul_f32 v[30:31], v[36:37], v[46:47]
	s_nop 1
	v_mov_b32_dpp v228, v30 row_ror:8 row_mask:0xf bank_mask:0xf
	v_mov_b32_dpp v229, v31 row_ror:8 row_mask:0xf bank_mask:0xf
	v_mov_b32_dpp v230, v32 row_ror:8 row_mask:0xf bank_mask:0xf
	v_mov_b32_dpp v231, v33 row_ror:8 row_mask:0xf bank_mask:0xf
	v_cndmask_b32_e64 v30, v228, v26, s[98:99]
	v_cndmask_b32_e64 v31, v229, v27, s[98:99]
	v_cndmask_b32_e64 v32, v230, v28, s[98:99]
	v_cndmask_b32_e64 v33, v231, v29, s[98:99]
	v_cndmask_b32_e64 v228, v26, v228, s[98:99]
	v_cndmask_b32_e64 v229, v27, v229, s[98:99]
	v_cndmask_b32_e64 v230, v28, v230, s[98:99]
	v_cndmask_b32_e64 v231, v29, v231, s[98:99]
	v_lshl_add_u64 v[232:233], v[40:41], 0, v[236:237]
	v_lshl_add_u64 v[234:235], v[40:41], 0, v[238:239]
	global_store_dwordx4 v[232:233], v[30:33], off sc0 sc1 nt
	global_store_dwordx4 v[234:235], v[228:231], off sc0 sc1 nt
	global_load_dwordx4 v[26:29], v[140:141], off offset:512
	s_nop 0
	global_load_dwordx4 v[30:33], v[140:141], off offset:528
	v_pk_mul_f32 v[22:23], v[22:23], v[42:43] op_sel_hi:[1,0]
	v_pk_mul_f32 v[20:21], v[20:21], v[42:43] op_sel_hi:[1,0]
	v_pk_mul_f32 v[34:35], v[18:19], v[42:43] op_sel_hi:[1,0]
	v_pk_mul_f32 v[36:37], v[16:17], v[42:43] op_sel_hi:[1,0]
	s_waitcnt vmcnt(1)
	v_pk_mul_f32 v[16:17], v[26:27], v[20:21]
	v_pk_mul_f32 v[18:19], v[28:29], v[22:23]
	s_waitcnt vmcnt(0)
	v_pk_mul_f32 v[20:21], v[30:31], v[36:37]
	v_pk_mul_f32 v[22:23], v[32:33], v[34:35]
	s_nop 1
	v_mov_b32_dpp v228, v20 row_ror:8 row_mask:0xf bank_mask:0xf
	v_mov_b32_dpp v229, v21 row_ror:8 row_mask:0xf bank_mask:0xf
	v_mov_b32_dpp v230, v22 row_ror:8 row_mask:0xf bank_mask:0xf
	v_mov_b32_dpp v231, v23 row_ror:8 row_mask:0xf bank_mask:0xf
	v_cndmask_b32_e64 v20, v228, v16, s[98:99]
	v_cndmask_b32_e64 v21, v229, v17, s[98:99]
	v_cndmask_b32_e64 v22, v230, v18, s[98:99]
	v_cndmask_b32_e64 v23, v231, v19, s[98:99]
	v_cndmask_b32_e64 v228, v16, v228, s[98:99]
	v_cndmask_b32_e64 v229, v17, v229, s[98:99]
	v_cndmask_b32_e64 v230, v18, v230, s[98:99]
	v_cndmask_b32_e64 v231, v19, v231, s[98:99]
	v_lshl_add_u64 v[232:233], v[40:41], 0, v[236:237]
	v_lshl_add_u64 v[234:235], v[40:41], 0, v[238:239]
	global_store_dwordx4 v[232:233], v[20:23], off offset:512 sc0 sc1 nt
	global_store_dwordx4 v[234:235], v[228:231], off offset:512 sc0 sc1 nt
	global_load_dword v26, v[112:113], off offset:704 sc1
	s_nop 0
	global_load_dwordx4 v[16:19], v[140:141], off
	global_load_dwordx4 v[20:23], v[140:141], off offset:16
	s_waitcnt vmcnt(2)
	v_fmac_f32_e32 v137, 0x3a800000, v26
	v_mul_f32_e32 v26, 0x4b800000, v137
	v_cmp_gt_f32_e32 vcc, s0, v137
	s_nop 1
	v_cndmask_b32_e32 v26, v137, v26, vcc
	v_rsq_f32_e32 v26, v26
	s_nop 0
	v_mul_f32_e32 v27, 0x45800000, v26
	v_cndmask_b32_e32 v26, v26, v27, vcc
	v_pk_mul_f32 v[12:13], v[12:13], v[26:27] op_sel_hi:[1,0]
	v_pk_mul_f32 v[14:15], v[14:15], v[26:27] op_sel_hi:[1,0]
	v_pk_mul_f32 v[28:29], v[8:9], v[26:27] op_sel_hi:[1,0]
	v_pk_mul_f32 v[30:31], v[10:11], v[26:27] op_sel_hi:[1,0]
	s_waitcnt vmcnt(1)
	v_pk_mul_f32 v[10:11], v[18:19], v[14:15]
	v_pk_mul_f32 v[8:9], v[16:17], v[12:13]
	s_waitcnt vmcnt(0)
	v_pk_mul_f32 v[14:15], v[22:23], v[30:31]
	v_pk_mul_f32 v[12:13], v[20:21], v[28:29]
	s_nop 1
	v_mov_b32_dpp v228, v12 row_ror:8 row_mask:0xf bank_mask:0xf
	v_mov_b32_dpp v229, v13 row_ror:8 row_mask:0xf bank_mask:0xf
	v_mov_b32_dpp v230, v14 row_ror:8 row_mask:0xf bank_mask:0xf
	v_mov_b32_dpp v231, v15 row_ror:8 row_mask:0xf bank_mask:0xf
	v_cndmask_b32_e64 v12, v228, v8, s[98:99]
	v_cndmask_b32_e64 v13, v229, v9, s[98:99]
	v_cndmask_b32_e64 v14, v230, v10, s[98:99]
	v_cndmask_b32_e64 v15, v231, v11, s[98:99]
	v_cndmask_b32_e64 v228, v8, v228, s[98:99]
	v_cndmask_b32_e64 v229, v9, v229, s[98:99]
	v_cndmask_b32_e64 v230, v10, v230, s[98:99]
	v_cndmask_b32_e64 v231, v11, v231, s[98:99]
	v_lshl_add_u64 v[232:233], v[24:25], 0, v[236:237]
	v_lshl_add_u64 v[234:235], v[24:25], 0, v[238:239]
	global_store_dwordx4 v[232:233], v[12:15], off sc0 sc1 nt
	global_store_dwordx4 v[234:235], v[228:231], off sc0 sc1 nt
	global_load_dwordx4 v[8:11], v[140:141], off offset:512
	s_nop 0
	global_load_dwordx4 v[12:15], v[140:141], off offset:528
	v_pk_mul_f32 v[6:7], v[6:7], v[26:27] op_sel_hi:[1,0]
	v_pk_mul_f32 v[4:5], v[4:5], v[26:27] op_sel_hi:[1,0]
	v_pk_mul_f32 v[16:17], v[2:3], v[26:27] op_sel_hi:[1,0]
	v_pk_mul_f32 v[18:19], v[0:1], v[26:27] op_sel_hi:[1,0]
	s_waitcnt vmcnt(1)
	v_pk_mul_f32 v[0:1], v[8:9], v[4:5]
	v_pk_mul_f32 v[2:3], v[10:11], v[6:7]
	s_waitcnt vmcnt(0)
	v_pk_mul_f32 v[4:5], v[12:13], v[18:19]
	v_pk_mul_f32 v[6:7], v[14:15], v[16:17]
	s_nop 1
	v_mov_b32_dpp v228, v4 row_ror:8 row_mask:0xf bank_mask:0xf
	v_mov_b32_dpp v229, v5 row_ror:8 row_mask:0xf bank_mask:0xf
	v_mov_b32_dpp v230, v6 row_ror:8 row_mask:0xf bank_mask:0xf
	v_mov_b32_dpp v231, v7 row_ror:8 row_mask:0xf bank_mask:0xf
	v_cndmask_b32_e64 v4, v228, v0, s[98:99]
	v_cndmask_b32_e64 v5, v229, v1, s[98:99]
	v_cndmask_b32_e64 v6, v230, v2, s[98:99]
	v_cndmask_b32_e64 v7, v231, v3, s[98:99]
	v_cndmask_b32_e64 v228, v0, v228, s[98:99]
	v_cndmask_b32_e64 v229, v1, v229, s[98:99]
	v_cndmask_b32_e64 v230, v2, v230, s[98:99]
	v_cndmask_b32_e64 v231, v3, v231, s[98:99]
	v_lshl_add_u64 v[232:233], v[24:25], 0, v[236:237]
	v_lshl_add_u64 v[234:235], v[24:25], 0, v[238:239]
	global_store_dwordx4 v[232:233], v[4:7], off offset:512 sc0 sc1 nt
	global_store_dwordx4 v[234:235], v[228:231], off offset:512 sc0 sc1 nt
